# v48 plus NA bias-table loads issued together and R1 B-fragment LDS reads batched per MFMA group
# baseline (speedup 1.0000x reference)
; #define LAS __attribute__((address_space(3)))
; __device__ __forceinline__ f32x16 zero16() { return (f32x16){0.f, 0.f, 0.f, 0.f, 0.f, 0.f, 0.f, 0.f, 0.f, 0.f, 0.f, 0.f, 0.f, 0.f, 0.f, 0.f}; }
; __device__ __forceinline__ void na_load(NaFrags& f, const bf16_t* __restrict__ proj, const bf16_t* __restrict__ projT, int ktok, int h, int c, int hh) {
;     const bf16_t* kp = proj + (size_t)(ktok + c) * NPROJ + 512 + h * 64 + 8 * hh;
; #pragma unroll
;     for (int s = 0; s < 4; ++s) f.k[s] = *(const bf16x8*)(kp + 16 * s);
; #pragma unroll
;     for (int dt = 0; dt < 2; ++dt)
; #pragma unroll
;         for (int s2 = 0; s2 < 2; ++s2) { const bf16_t* vp = projT + (size_t)(h * 64 + dt * 32 + c) * MG + (ktok + 16 * s2 + 4 * hh);
;             f.v[dt][s2][0] = *(const u32x2*)vp; f.v[dt][s2][1] = *(const u32x2*)(vp + 8); }
; }
; __device__ __forceinline__ void na_item(const bf16_t* __restrict__ proj, const bf16_t* __restrict__ projT, bf16_t* aout, const float* __restrict__ relb  , int item, int seqlen, LAS unsigned char* lds, int w, int lane) {
;     const int c = lane & 31, hh = lane >> 5;
;     const int R = item >> 3, h = item & 7;
;     const int rps = seqlen >> 6, seq = R / rps, r = R % rps;
;     int rs = r - 4; rs = rs < 0 ? 0 : rs; rs = rs > rps - 8 ? rps - 8 : rs;
;     const int qtok0 = seq * seqlen + r * 64, ktok0 = seq * seqlen + rs * 64;
;     LAS float* bias = (LAS float*)(lds + w * NA_LDS_WAVE) + 64;
;     LAS bf16_t* Otile = (LAS bf16_t*)(lds + w * NA_LDS_WAVE + 3072);
;     for (int i = lane; i < 768; i += 64) { const int j = i - 64; bias[j] = (j >= 0 && j < 465) ? relb[h * 465 + j] * 1.4426950408889634f : 0.f; }
;     bf16x8 qf[2][4];
; #pragma unroll
;     for (int qh = 0; qh < 2; ++qh) { const bf16_t* qp = proj + (size_t)(qtok0 + 32 * qh + c) * NPROJ + h * 64 + 8 * hh;
; #pragma unroll
;         for (int s = 0; s < 4; ++s) qf[qh][s] = *(const bf16x8*)(qp + 16 * s); }
;     f32x16 O[2][2];
;     float mrun[2], lrun[2]; int cs[2];
; #pragma unroll
;     for (int qh = 0; qh < 2; ++qh) { O[qh][0] = zero16(); O[qh][1] = zero16(); mrun[qh] = -1e30f; lrun[qh] = 0.f;
;         int x = 32 * qh + c - 8; x = x < 0 ? 0 : x; x = x > 48 ? 48 : x; cs[qh] = x; }
;     NaFrags cur, nxt;
;     na_load(cur, proj, projT, ktok0, h, c, hh);
.LBB0_347:
	s_mov_b64 s[0:1], 0
	s_mov_b64 s[6:7], 0
	s_mov_b64 s[4:5], 0
	v_add_u32_e32 v3, 64, v200
	v_add_u32_e32 v0, s42, v3
	v_lshl_add_u64 v[4:5], v[0:1], 2, s[8:9]
	v_mov_b32_e32 v13, 0
	v_mov_b32_e32 v14, 0
	global_load_dword v6, v[4:5], off
	global_load_dword v7, v[4:5], off offset:256
	global_load_dword v8, v[4:5], off offset:512
	global_load_dword v9, v[4:5], off offset:768
	global_load_dword v10, v[4:5], off offset:1024
	global_load_dword v11, v[4:5], off offset:1280
	global_load_dword v12, v[4:5], off offset:1536
	v_cmp_gt_u32_e32 vcc, 17, v3
	s_and_saveexec_b64 s[40:41], vcc
	global_load_dword v13, v[4:5], off offset:1792
	s_or_b64 exec, exec, s[40:41]
	s_waitcnt vmcnt(0)
	v_mul_f32_e32 v6, 0x3fb8aa3b, v6
	v_mul_f32_e32 v7, 0x3fb8aa3b, v7
	v_mul_f32_e32 v8, 0x3fb8aa3b, v8
	v_mul_f32_e32 v9, 0x3fb8aa3b, v9
	v_mul_f32_e32 v10, 0x3fb8aa3b, v10
	v_mul_f32_e32 v11, 0x3fb8aa3b, v11
	v_mul_f32_e32 v12, 0x3fb8aa3b, v12
	v_mul_f32_e32 v13, 0x3fb8aa3b, v13
	ds_write_b32 v201, v14
	ds_write_b32 v201, v6 offset:256
	ds_write_b32 v201, v7 offset:512
	ds_write_b32 v201, v8 offset:768
	ds_write_b32 v201, v9 offset:1024
	ds_write_b32 v201, v10 offset:1280
	ds_write_b32 v201, v11 offset:1536
	ds_write_b32 v201, v12 offset:1792
	ds_write_b32 v201, v13 offset:2048
	ds_write_b32 v201, v14 offset:2304
	ds_write_b32 v201, v14 offset:2560
	ds_write_b32 v201, v14 offset:2816
	s_add_u32 s10, s30, s0
	s_addc_u32 s11, s31, s1
	s_add_u32 s0, s30, s6
	s_addc_u32 s1, s31, s7
	s_ashr_i32 s6, s25, 3
	s_abs_i32 s16, s6
	s_mul_hi_u32 s17, s16, s15
	s_mul_i32 s28, s17, s74
	s_sub_i32 s16, s16, s28
	s_ashr_i32 s7, s25, 31
	s_add_i32 s28, s17, 1
	s_sub_i32 s29, s16, s74
	s_cmp_ge_u32 s16, s74
	s_cselect_b32 s17, s28, s17
	s_cselect_b32 s16, s29, s16
	s_add_i32 s28, s17, 1
	s_cmp_ge_u32 s16, s74
	s_cselect_b32 s16, s28, s17
	s_xor_b32 s16, s16, s7
	s_sub_i32 s7, s16, s7
	s_mul_i32 s16, s7, s74
	s_sub_i32 s28, s6, s16
	s_max_i32 s6, s28, 4
	s_add_i32 s6, s6, -4
	s_lshl_b32 s16, s28, 6
	s_add_u32 s10, s10, 0xe240000
	s_addc_u32 s11, s11, 0
	s_min_u32 s29, s6, s75
	s_lshl_b32 s17, s29, 6
	s_lshl_b32 s7, s7, s70
	s_add_i32 s6, s7, s16
	s_add_i32 s33, s7, s17
	s_lshl_b32 s58, s43, 1
	s_add_u32 s16, s10, s58
	s_addc_u32 s17, s11, 0
	v_mov_b32_e32 v163, v1
	v_or_b32_e32 v0, s6, v190
	v_lshl_add_u64 v[168:169], s[16:17], 0, v[162:163]
	v_mad_i64_i32 v[2:3], s[16:17], v0, s18, v[168:169]
	v_or_b32_e32 v0, 32, v0
	global_load_dwordx4 v[82:85], v[2:3], off
	global_load_dwordx4 v[86:89], v[2:3], off offset:32
	global_load_dwordx4 v[90:93], v[2:3], off offset:64
	global_load_dwordx4 v[94:97], v[2:3], off offset:96
	v_mad_i64_i32 v[2:3], s[16:17], v0, s18, v[168:169]
	global_load_dwordx4 v[98:101], v[2:3], off
	global_load_dwordx4 v[102:105], v[2:3], off offset:32
	global_load_dwordx4 v[106:109], v[2:3], off offset:64
	global_load_dwordx4 v[110:113], v[2:3], off offset:96
	v_add_u32_e32 v0, s33, v202
	v_xor_b32_e32 v0, 32, v0
	v_mov_b64_e32 v[2:3], s[10:11]
	v_mad_i64_i32 v[2:3], s[10:11], v0, s18, v[2:3]
	v_lshl_add_u64 v[2:3], v[2:3], 0, s[58:59]
	v_lshl_add_u64 v[2:3], v[2:3], 0, v[162:163]
	global_load_dwordx4 v[158:161], v[2:3], off offset:1024
	global_load_dwordx4 v[154:157], v[2:3], off offset:1056
	global_load_dwordx4 v[150:153], v[2:3], off offset:1088
	global_load_dwordx4 v[146:149], v[2:3], off offset:1120
	v_or_b32_e32 v2, s33, v196
	v_mov_b32_e32 v165, v1
	v_ashrrev_i32_e32 v3, 31, v2
	v_lshl_add_u64 v[4:5], s[0:1], 0, v[164:165]
	s_mov_b64 s[0:1], 0x18340000
	v_lshl_add_u64 v[170:171], v[4:5], 0, s[60:61]
	v_lshlrev_b64 v[6:7], 1, v[2:3]
	v_or_b32_e32 v2, 16, v2
	v_mbcnt_lo_u32_b32 v2, -1, 0
	v_mbcnt_hi_u32_b32 v2, -1, v2
	v_lshrrev_b32_e32 v3, 3, v2
	v_sub_u32_e32 v3, v3, v190
	s_mov_b32 s16, 0x8000
	v_mad_i64_i32 v[172:173], s[40:41], v3, s16, v[170:171]
	v_and_b32_e32 v2, 7, v2
	v_lshlrev_b32_e32 v2, 4, v2
	s_lshl_b32 s16, s33, 1
	v_add_u32_e32 v2, s16, v2
	v_mov_b32_e32 v3, 0
	v_lshl_add_u64 v[172:173], v[172:173], 0, v[2:3]
	v_mov_b64_e32 v[2:3], v[172:173]
	s_mov_b32 s38, 0x40000
	s_mov_b32 s39, 0
	s_add_i32 m0, s27, 0xc00
	s_nop 0
	global_load_lds_dwordx4 v[2:3], off
	s_add_i32 m0, m0, 0x400
	v_lshl_add_u64 v[2:3], v[2:3], 0, s[38:39]
	global_load_lds_dwordx4 v[2:3], off
	s_add_i32 m0, m0, 0x400
	v_lshl_add_u64 v[2:3], v[2:3], 0, s[38:39]
	global_load_lds_dwordx4 v[2:3], off
	s_add_i32 m0, m0, 0x400
	v_lshl_add_u64 v[2:3], v[2:3], 0, s[38:39]
	global_load_lds_dwordx4 v[2:3], off
	s_add_i32 m0, m0, 0x400
	v_lshl_add_u64 v[2:3], v[2:3], 0, s[38:39]
	global_load_lds_dwordx4 v[2:3], off
	s_add_i32 m0, m0, 0x400
	v_lshl_add_u64 v[2:3], v[2:3], 0, s[38:39]
	global_load_lds_dwordx4 v[2:3], off
	s_add_i32 m0, m0, 0x400
	v_lshl_add_u64 v[2:3], v[2:3], 0, s[38:39]
	global_load_lds_dwordx4 v[2:3], off
	s_add_i32 m0, m0, 0x400
	v_lshl_add_u64 v[2:3], v[2:3], 0, s[38:39]
	global_load_lds_dwordx4 v[2:3], off
	v_mov_b32_e32 v14, v1
	v_mov_b32_e32 v15, v1
	v_mov_b32_e32 v0, v1
	v_mov_b32_e32 v2, v1
	v_mov_b32_e32 v3, v1
	v_mov_b32_e32 v4, v1
	v_mov_b32_e32 v5, v1
	v_mov_b32_e32 v6, v1
	v_mov_b32_e32 v7, v1
	v_mov_b32_e32 v8, v1
	v_mov_b32_e32 v9, v1
	v_mov_b32_e32 v10, v1
	v_mov_b32_e32 v11, v1
	v_mov_b32_e32 v12, v1
	v_mov_b32_e32 v13, v1
	v_mov_b64_e32 v[48:49], v[14:15]
	v_mov_b64_e32 v[64:65], v[14:15]
	v_mov_b64_e32 v[32:33], v[14:15]
	v_mov_b64_e32 v[46:47], v[12:13]
	v_mov_b64_e32 v[44:45], v[10:11]
	v_mov_b64_e32 v[42:43], v[8:9]
	v_mov_b64_e32 v[40:41], v[6:7]
	v_mov_b64_e32 v[38:39], v[4:5]
	v_mov_b64_e32 v[36:37], v[2:3]
	v_mov_b64_e32 v[34:35], v[0:1]
	v_mov_b64_e32 v[62:63], v[12:13]
	v_mov_b64_e32 v[60:61], v[10:11]
	v_mov_b64_e32 v[58:59], v[8:9]
	v_mov_b64_e32 v[56:57], v[6:7]
	v_mov_b64_e32 v[54:55], v[4:5]
	v_mov_b64_e32 v[52:53], v[2:3]
	v_mov_b64_e32 v[50:51], v[0:1]
	v_mov_b64_e32 v[30:31], v[12:13]
	v_mov_b64_e32 v[28:29], v[10:11]
	v_mov_b64_e32 v[26:27], v[8:9]
	v_mov_b64_e32 v[24:25], v[6:7]
	v_mov_b64_e32 v[22:23], v[4:5]
	v_mov_b64_e32 v[20:21], v[2:3]
	v_mov_b64_e32 v[18:19], v[0:1]
	v_mov_b64_e32 v[16:17], v[14:15]
	s_sub_i32 s7, s29, s28
	v_add_u32_e32 v165, s33, v196
	v_add_u32_e32 v167, s33, v202
	s_mov_b32 s28, 0
	v_mov_b32_e32 v163, 0
	v_mov_b32_e32 v207, 0xf149f2ca
	v_mov_b32_e32 v208, 0xf149f2ca
	v_mov_b32_e32 v206, 0
	v_mov_b64_e32 v[14:15], v[12:13]
	v_mov_b64_e32 v[12:13], v[10:11]
	v_mov_b64_e32 v[10:11], v[8:9]
	v_mov_b64_e32 v[8:9], v[6:7]
	v_mov_b64_e32 v[6:7], v[4:5]
	v_mov_b64_e32 v[4:5], v[2:3]
	v_mov_b64_e32 v[2:3], v[0:1]
	s_mov_b32 s29, 0
	s_cmpk_eq_i32 s28, 0x1e0
	s_cbranch_scc1 .LBB0_354
	s_branch .LBB0_353

; #define LAS __attribute__((address_space(3)))
; __device__ __forceinline__ void unpack8(const u32x4 w, float* f) { f[0] = bf_lo(w.x); f[1] = bf_hi(w.x); f[2] = bf_lo(w.y); f[3] = bf_hi(w.y); f[4] = bf_lo(w.z); f[5] = bf_hi(w.z); f[6] = bf_lo(w.w); f[7] = bf_hi(w.w); }
; __device__ __forceinline__ void r1_item(const bf16_t* __restrict__ projT, bf16_t* stloc, const float* __restrict__ cosT, const float* __restrict__ sinT, float lgf2, float lgb2, int item, int seqlen, LAS unsigned char* lds) {
;     const int tid = otid(), w = __builtin_amdgcn_readfirstlane(tid >> 6), lane = tid & 63, c = lane & 31, hh = lane >> 5;
;     const int ch = item >> 2, h = item & 3, tok0 = ch * 128, pos0 = tok0 % seqlen;
;     LAS bf16_t* KTf = (LAS bf16_t*)lds; LAS bf16_t* KTb = (LAS bf16_t*)(lds + 128 * KT_STRIDE * 2);
;     const float scale = 0.08838834764831845f;
;     bf16x8 af[8];
;     { const bf16_t* vp = projT + (size_t)(1024 + h * 256 + 32 * w + c) * MG + tok0 + 8 * hh;
; #pragma unroll
;       for (int s = 0; s < 8; ++s) af[s] = *(const bf16x8*)(vp + 16 * s); }
; #pragma unroll
;     for (int it = 0; it < 2; ++it) {
;         const int id = tid + NTHREADS * it, d = id >> 4, t8 = id & 15;
;         float k1[8], k2[8];
;         unpack8(__builtin_nontemporal_load((const u32x4*)(projT + (size_t)(512 + h * 128 + d) * MG + tok0 + 8 * t8)), k1);
;         unpack8(__builtin_nontemporal_load((const u32x4*)(projT + (size_t)(512 + h * 128 + d + 64) * MG + tok0 + 8 * t8)), k2);
;         const f32x4 c0 = *(const f32x4*)(cosT + (size_t)d * 16384 + pos0 + 8 * t8), c1 = *(const f32x4*)(cosT + (size_t)d * 16384 + pos0 + 8 * t8 + 4);
;         const f32x4 s0 = *(const f32x4*)(sinT + (size_t)d * 16384 + pos0 + 8 * t8), s1 = *(const f32x4*)(sinT + (size_t)d * 16384 + pos0 + 8 * t8 + 4);
;         float f1[8], f2[8], b1[8], b2[8];
; #pragma unroll
;         for (int j = 0; j < 8; ++j) { const float cv = j < 4 ? c0[j & 3] : c1[j & 3], sv = j < 4 ? s0[j & 3] : s1[j & 3];
;             const float r1 = (k1[j] * cv - k2[j] * sv) * scale, r2 = (k1[j] * sv + k2[j] * cv) * scale;
;             const int tl = 8 * t8 + j; const float df = __builtin_amdgcn_exp2f((float)(127 - tl) * lgf2), db = __builtin_amdgcn_exp2f((float)tl * lgb2);
;             f1[j] = r1 * df; f2[j] = r2 * df; b1[j] = r1 * db; b2[j] = r2 * db; }
.LBB0_361:
	s_mov_b64 s[6:7], 0
	s_add_u32 s10, s30, s6
	s_addc_u32 s11, s31, s7
	s_and_b32 s6, s27, 6
	s_or_b32 s58, s6, s76
	s_lshl_b64 s[6:7], s[58:59], 2
	s_add_u32 s6, s10, s6
	s_addc_u32 s7, s11, s7
	global_load_dwordx2 v[66:67], v244, s[6:7]
	s_mov_b64 s[6:7], 0
	s_add_u32 s6, s30, s6
	s_addc_u32 s7, s31, s7
	s_add_u32 s40, s6, 0x18240000
	s_addc_u32 s41, s7, 0
	s_mov_b64 s[6:7], 0
	s_mov_b64 s[10:11], 0
	s_add_u32 s17, s30, s10
	s_addc_u32 s34, s31, s11
	s_mov_b64 s[28:29], 0
	s_add_u32 s11, s30, s28
	v_mov_b32_e32 v70, v232
	s_addc_u32 s16, s31, s29
	s_and_b32 s28, s25, 0xffffff80
	v_readfirstlane_b32 s10, v70
	s_ashr_i32 s43, s10, 1
	s_ashr_i32 s29, s28, 31
	s_ashr_i32 s10, s25, 31
	s_lshl_b64 s[38:39], s[28:29], 1
	s_add_i32 s28, s28, s10
	s_xor_b32 s28, s28, s10
	s_mul_hi_u32 s29, s28, s67
	s_mul_i32 s29, s29, s71
	s_sub_i32 s28, s28, s29
	s_and_b32 s33, s42, 3
	s_andn2_b32 s43, s43, 31
	s_sub_i32 s29, s28, s71
	s_cmp_ge_u32 s28, s71
	s_cselect_b32 s28, s29, s28
	v_and_b32_e32 v118, 31, v70
	s_sub_i32 s29, s28, s71
	v_lshl_or_b32 v0, s33, 8, v118
	s_cmp_ge_u32 s28, s71
	v_add_u32_e32 v0, s43, v0
	s_cselect_b32 s28, s29, s28
	v_add_u32_e32 v2, 0x400, v0
	s_xor_b32 s28, s28, s10
	v_ashrrev_i32_e32 v3, 31, v2
	s_sub_i32 s28, s28, s10
	s_lshl_b32 s10, s33, 7
	v_lshlrev_b64 v[2:3], 15, v[2:3]
	s_bitset1_b32 s10, 9
	v_bfe_u32 v51, v70, 5, 1
	v_lshl_add_u64 v[2:3], s[40:41], 0, v[2:3]
	s_add_u32 s40, s40, s38
	v_lshl_add_u64 v[2:3], v[2:3], 0, s[38:39]
	v_lshlrev_b32_e32 v0, 4, v51
	s_addc_u32 s41, s41, s39
	v_lshlrev_b32_e32 v71, 3, v70
	s_ashr_i32 s29, s28, 31
	v_lshl_add_u64 v[2:3], v[2:3], 0, v[0:1]
	v_and_b32_e32 v72, 0x78, v71
	s_lshl_b64 s[28:29], s[28:29], 2
	global_load_dwordx4 v[46:49], v[2:3], off
	global_load_dwordx4 v[42:45], v[2:3], off offset:32
	global_load_dwordx4 v[38:41], v[2:3], off offset:64
	global_load_dwordx4 v[34:37], v[2:3], off offset:96
	global_load_dwordx4 v[30:33], v[2:3], off offset:128
	global_load_dwordx4 v[26:29], v[2:3], off offset:160
	global_load_dwordx4 v[22:25], v[2:3], off offset:192
	global_load_dwordx4 v[18:21], v[2:3], off offset:224
	v_lshlrev_b32_e32 v2, 1, v72
	v_mov_b32_e32 v3, v1
	s_add_u32 s38, s17, s28
	v_ashrrev_i32_e32 v68, 4, v70
	v_lshl_add_u64 v[56:57], s[40:41], 0, v[2:3]
	s_addc_u32 s39, s34, s29
	v_add_u32_e32 v50, 0, v2
	v_add_u32_e32 v2, s10, v68
	s_add_u32 s28, s11, s28
	v_ashrrev_i32_e32 v3, 31, v2
	v_lshlrev_b32_e32 v4, 2, v72
	v_mov_b32_e32 v5, v1
	s_addc_u32 s29, s16, s29
	v_lshlrev_b64 v[2:3], 15, v[2:3]
	v_lshl_add_u64 v[6:7], s[38:39], 0, v[4:5]
	s_mov_b64 s[38:39], 0xc40000
	v_lshl_add_u64 v[4:5], s[28:29], 0, v[4:5]
	s_mov_b64 s[16:17], 0x1040000
	v_lshl_add_u64 v[2:3], v[56:57], 0, v[2:3]
	v_ashrrev_i32_e32 v69, 31, v68
	v_lshl_add_u64 v[52:53], v[6:7], 0, s[38:39]
	v_lshl_add_u64 v[54:55], v[4:5], 0, s[16:17]
	global_load_dwordx4 v[6:9], v[2:3], off nt
	v_add_co_u32_e32 v2, vcc, s13, v2
	v_lshlrev_b64 v[14:15], 16, v[68:69]
	s_nop 0
	v_addc_co_u32_e32 v3, vcc, 0, v3, vcc
	v_lshl_add_u64 v[16:17], v[52:53], 0, v[14:15]
	v_lshl_add_u64 v[58:59], v[54:55], 0, v[14:15]
	global_load_dwordx4 v[10:13], v[2:3], off nt
	s_nop 0
	global_load_dwordx4 v[2:5], v[16:17], off offset:16
	global_load_dwordx4 v[74:77], v[16:17], off
	s_nop 0
	global_load_dwordx4 v[14:17], v[58:59], off offset:16
	global_load_dwordx4 v[78:81], v[58:59], off
	v_add_u32_e32 v190, 0x200, v70
	v_ashrrev_i32_e32 v192, 4, v190
	v_add_u32_e32 v190, s10, v192
	v_ashrrev_i32_e32 v191, 31, v190
	v_lshlrev_b64 v[190:191], 15, v[190:191]
	v_lshl_add_u64 v[190:191], v[56:57], 0, v[190:191]
	global_load_dwordx4 v[196:199], v[190:191], off nt
	v_add_co_u32_e32 v190, vcc, s13, v190
	v_ashrrev_i32_e32 v193, 31, v192
	s_nop 0
	v_addc_co_u32_e32 v191, vcc, 0, v191, vcc
	global_load_dwordx4 v[200:203], v[190:191], off nt
	v_lshlrev_b64 v[190:191], 16, v[192:193]
	v_lshl_add_u64 v[194:195], v[52:53], 0, v[190:191]
	v_lshl_add_u64 v[190:191], v[54:55], 0, v[190:191]
	global_load_dwordx4 v[204:207], v[194:195], off offset:16
	global_load_dwordx4 v[208:211], v[194:195], off
	global_load_dwordx4 v[212:215], v[190:191], off offset:16
	global_load_dwordx4 v[216:219], v[190:191], off
	s_movk_i32 s11, 0x7f
	v_bitop3_b32 v58, v71, s11, v242 bitop3:0x6c
	v_cvt_f32_ubyte0_e32 v58, v58
	s_movk_i32 s11, 0x7e
	s_waitcnt vmcnt(20)
	v_mul_f32_e32 v58, v66, v58
	v_or_b32_e32 v59, 1, v72
	v_bitop3_b32 v61, v71, s11, v242 bitop3:0x6c
	v_exp_f32_e32 v60, v58
	v_cvt_f32_ubyte0_e32 v58, v72
	v_cvt_f32_ubyte0_e32 v61, v61
	v_cvt_f32_ubyte0_e32 v59, v59
	v_mul_f32_e32 v58, v67, v58
	v_mul_f32_e32 v61, v66, v61
	v_mul_f32_e32 v59, v67, v59
	v_exp_f32_e32 v58, v58
	v_exp_f32_e32 v61, v61
	v_exp_f32_e32 v59, v59
	s_movk_i32 s11, 0x7d
	s_add_u32 s6, s0, s6
	s_addc_u32 s7, s1, s7
	s_add_i32 s42, s42, s52
	s_add_i32 s27, s27, s21
	s_add_i32 s25, s25, s22
	s_waitcnt vmcnt(11)
	v_lshlrev_b32_e32 v62, 16, v6
	v_and_b32_e32 v63, 0xffff0000, v6
	v_or_b32_e32 v6, 2, v72
	v_cvt_f32_ubyte0_e32 v6, v6
	v_mul_f32_e32 v6, v67, v6
	v_lshlrev_b32_e32 v90, 16, v8
	v_and_b32_e32 v91, 0xffff0000, v8
	v_or_b32_e32 v8, 7, v72
	s_waitcnt vmcnt(10)
	v_lshlrev_b32_e32 v64, 16, v10
	v_and_b32_e32 v65, 0xffff0000, v10
	s_waitcnt vmcnt(6)
; #define LAS __attribute__((address_space(3)))
; __device__ __forceinline__ void unpack8(const u32x4 w, float* f) { f[0] = bf_lo(w.x); f[1] = bf_hi(w.x); f[2] = bf_lo(w.y); f[3] = bf_hi(w.y); f[4] = bf_lo(w.z); f[5] = bf_hi(w.z); f[6] = bf_lo(w.w); f[7] = bf_hi(w.w); }
; __device__ __forceinline__ u32x4 pack8(const float* f) { u32x4 w; w.x = cvt_pk_bf16(f[0], f[1]); w.y = cvt_pk_bf16(f[2], f[3]); w.z = cvt_pk_bf16(f[4], f[5]); w.w = cvt_pk_bf16(f[6], f[7]); return w; }
; __device__ __forceinline__ void r1_item(const bf16_t* __restrict__ projT, bf16_t* stloc, const float* __restrict__ cosT, const float* __restrict__ sinT, float lgf2, float lgb2, int item, int seqlen, LAS unsigned char* lds) {
;     ...
;         const int id = tid + NTHREADS * it, d = id >> 4, t8 = id & 15;
;         float k1[8], k2[8];
;         unpack8(__builtin_nontemporal_load((const u32x4*)(projT + (size_t)(512 + h * 128 + d) * MG + tok0 + 8 * t8)), k1);
;         unpack8(__builtin_nontemporal_load((const u32x4*)(projT + (size_t)(512 + h * 128 + d + 64) * MG + tok0 + 8 * t8)), k2);
;         const f32x4 c0 = *(const f32x4*)(cosT + (size_t)d * 16384 + pos0 + 8 * t8), c1 = *(const f32x4*)(cosT + (size_t)d * 16384 + pos0 + 8 * t8 + 4);
;         const f32x4 s0 = *(const f32x4*)(sinT + (size_t)d * 16384 + pos0 + 8 * t8), s1 = *(const f32x4*)(sinT + (size_t)d * 16384 + pos0 + 8 * t8 + 4);
;         float f1[8], f2[8], b1[8], b2[8];
; #pragma unroll
;         for (int j = 0; j < 8; ++j) { const float cv = j < 4 ? c0[j & 3] : c1[j & 3], sv = j < 4 ? s0[j & 3] : s1[j & 3];
;             const float r1 = (k1[j] * cv - k2[j] * sv) * scale, r2 = (k1[j] * sv + k2[j] * cv) * scale;
;             const int tl = 8 * t8 + j; const float df = __builtin_amdgcn_exp2f((float)(127 - tl) * lgf2), db = __builtin_amdgcn_exp2f((float)tl * lgb2);
;             f1[j] = r1 * df; f2[j] = r2 * df; b1[j] = r1 * db; b2[j] = r2 * db; }
;         *(LAS u32x4*)(KTf + d * KT_STRIDE + 8 * t8) = pack8(f1); *(LAS u32x4*)(KTf + (d + 64) * KT_STRIDE + 8 * t8) = pack8(f2);
;         *(LAS u32x4*)(KTb + d * KT_STRIDE + 8 * t8) = pack8(b1); *(LAS u32x4*)(KTb + (d + 64) * KT_STRIDE + 8 * t8) = pack8(b2);
;     }
	v_pk_mul_f32 v[82:83], v[78:79], v[62:63]
	v_bitop3_b32 v10, v71, s11, v242 bitop3:0x6c
	v_pk_fma_f32 v[82:83], v[74:75], v[64:65], v[82:83]
	v_pk_mul_f32 v[64:65], v[78:79], v[64:65]
	v_cvt_f32_ubyte0_e32 v10, v10
	v_pk_fma_f32 v[62:63], v[74:75], v[62:63], v[64:65] neg_lo:[0,0,1] neg_hi:[0,0,1]
	v_mul_f32_e32 v10, v66, v10
	v_pk_mul_f32 v[62:63], v[62:63], s[64:65] op_sel_hi:[1,0]
	s_movk_i32 s11, 0x7c
	v_pk_mul_f32 v[74:75], v[60:61], v[62:63]
	v_pk_mul_f32 v[78:79], v[58:59], v[62:63]
	v_exp_f32_e32 v62, v6
	v_or_b32_e32 v6, 3, v72
	v_exp_f32_e32 v64, v10
	v_bitop3_b32 v10, v71, s11, v242 bitop3:0x6c
	v_cvt_f32_ubyte0_e32 v6, v6
	v_cvt_f32_ubyte0_e32 v10, v10
	v_mul_f32_e32 v6, v67, v6
	v_mul_f32_e32 v10, v66, v10
	v_exp_f32_e32 v63, v6
	v_lshlrev_b32_e32 v6, 16, v7
	v_and_b32_e32 v7, 0xffff0000, v7
	v_exp_f32_e32 v65, v10
	v_lshlrev_b32_e32 v10, 16, v11
	v_and_b32_e32 v11, 0xffff0000, v11
	v_pk_mul_f32 v[86:87], v[80:81], v[6:7]
	s_movk_i32 s11, 0x7b
	v_pk_fma_f32 v[86:87], v[76:77], v[10:11], v[86:87]
	v_pk_mul_f32 v[10:11], v[80:81], v[10:11]
	v_lshlrev_b32_e32 v92, 16, v12
	v_pk_fma_f32 v[6:7], v[76:77], v[6:7], v[10:11] neg_lo:[0,0,1] neg_hi:[0,0,1]
	v_or_b32_e32 v11, 5, v72
	v_pk_mul_f32 v[6:7], v[6:7], s[64:65] op_sel_hi:[1,0]
	v_cvt_f32_ubyte0_e32 v11, v11
	v_pk_mul_f32 v[76:77], v[64:65], v[6:7]
	v_pk_mul_f32 v[80:81], v[62:63], v[6:7]
	v_or_b32_e32 v7, 4, v72
	v_cvt_f32_ubyte0_e32 v7, v7
	v_bitop3_b32 v6, v71, s11, v242 bitop3:0x6c
	v_mul_f32_e32 v7, v67, v7
	s_movk_i32 s11, 0x7a
	v_exp_f32_e32 v10, v7
	v_bitop3_b32 v7, v71, s11, v242 bitop3:0x6c
	v_cvt_f32_ubyte0_e32 v6, v6
	v_cvt_f32_ubyte0_e32 v7, v7
	v_mul_f32_e32 v6, v66, v6
	v_mul_f32_e32 v7, v66, v7
	v_mul_f32_e32 v11, v67, v11
	v_exp_f32_e32 v6, v6
	v_exp_f32_e32 v7, v7
	v_exp_f32_e32 v11, v11
	v_and_b32_e32 v93, 0xffff0000, v12
	v_pk_mul_f32 v[94:95], v[14:15], v[90:91]
	v_pk_mul_f32 v[14:15], v[14:15], v[92:93]
	v_pk_fma_f32 v[94:95], v[2:3], v[92:93], v[94:95]
	v_pk_fma_f32 v[2:3], v[2:3], v[90:91], v[14:15] neg_lo:[0,0,1] neg_hi:[0,0,1]
	s_movk_i32 s11, 0x79
	v_pk_mul_f32 v[2:3], v[2:3], s[64:65] op_sel_hi:[1,0]
	v_cvt_f32_ubyte0_e32 v8, v8
	v_pk_mul_f32 v[90:91], v[6:7], v[2:3]
	v_pk_mul_f32 v[92:93], v[10:11], v[2:3]
	v_or_b32_e32 v3, 6, v72
	v_cvt_f32_ubyte0_e32 v3, v3
	v_bitop3_b32 v2, v71, s11, v242 bitop3:0x6c
	v_mul_f32_e32 v3, v67, v3
	s_movk_i32 s11, 0x78
	v_exp_f32_e32 v14, v3
	v_bitop3_b32 v3, v71, s11, v71 bitop3:0xc
	v_cvt_f32_ubyte0_e32 v2, v2
	v_cvt_f32_ubyte0_e32 v3, v3
	v_mul_f32_e32 v8, v67, v8
	v_mul_f32_e32 v2, v66, v2
	v_mul_f32_e32 v3, v66, v3
	v_exp_f32_e32 v15, v8
	v_lshlrev_b32_e32 v8, 16, v9
	v_and_b32_e32 v9, 0xffff0000, v9
	v_exp_f32_e32 v2, v2
	v_exp_f32_e32 v3, v3
	v_lshlrev_b32_e32 v12, 16, v13
	v_and_b32_e32 v13, 0xffff0000, v13
	v_pk_mul_f32 v[66:67], v[16:17], v[8:9]
	v_pk_mul_f32 v[82:83], v[82:83], s[64:65] op_sel_hi:[1,0]
	v_pk_fma_f32 v[66:67], v[4:5], v[12:13], v[66:67]
	v_pk_mul_f32 v[12:13], v[16:17], v[12:13]
	v_pk_mul_f32 v[86:87], v[86:87], s[64:65] op_sel_hi:[1,0]
	v_pk_fma_f32 v[4:5], v[4:5], v[8:9], v[12:13] neg_lo:[0,0,1] neg_hi:[0,0,1]
	v_pk_mul_f32 v[94:95], v[94:95], s[64:65] op_sel_hi:[1,0]
	v_pk_mul_f32 v[66:67], v[66:67], s[64:65] op_sel_hi:[1,0]
	v_pk_mul_f32 v[4:5], v[4:5], s[64:65] op_sel_hi:[1,0]
	v_pk_mul_f32 v[84:85], v[60:61], v[82:83]
	v_pk_mul_f32 v[88:89], v[64:65], v[86:87]
	v_pk_mul_f32 v[96:97], v[6:7], v[94:95]
	v_pk_mul_f32 v[98:99], v[2:3], v[66:67]
	v_pk_mul_f32 v[8:9], v[2:3], v[4:5]
	v_pk_mul_f32 v[4:5], v[14:15], v[4:5]
	v_pk_mul_f32 v[12:13], v[14:15], v[66:67]
	v_cvt_pk_bf16_f32 v72, v74, v75
	v_cvt_pk_bf16_f32 v75, v8, v9
	v_mad_u64_u32 v[8:9], s[16:17], v68, s12, v[50:51]
	v_cvt_pk_bf16_f32 v66, v84, v85
	v_cvt_pk_bf16_f32 v67, v88, v89
	v_cvt_pk_bf16_f32 v68, v96, v97
	v_cvt_pk_bf16_f32 v69, v98, v99
	v_pk_mul_f32 v[82:83], v[58:59], v[82:83]
	v_pk_mul_f32 v[86:87], v[62:63], v[86:87]
	v_pk_mul_f32 v[94:95], v[10:11], v[94:95]
	ds_write_b128 v8, v[66:69] offset:17408
	v_cvt_pk_bf16_f32 v66, v78, v79
	v_cvt_pk_bf16_f32 v67, v80, v81
	v_cvt_pk_bf16_f32 v68, v92, v93
	v_cvt_pk_bf16_f32 v69, v4, v5
	v_cvt_pk_bf16_f32 v73, v76, v77
	v_cvt_pk_bf16_f32 v74, v90, v91
	ds_write_b128 v8, v[66:69] offset:34816
	v_cvt_pk_bf16_f32 v66, v82, v83
	v_cvt_pk_bf16_f32 v67, v86, v87
	v_cvt_pk_bf16_f32 v68, v94, v95
	v_cvt_pk_bf16_f32 v69, v12, v13
	v_add_u32_e32 v4, 0x200, v70
	ds_write_b128 v8, v[72:75]
	ds_write_b128 v8, v[66:69] offset:52224
	v_ashrrev_i32_e32 v8, 4, v4
	v_add_u32_e32 v4, s10, v8
	v_ashrrev_i32_e32 v5, 31, v4
	v_lshlrev_b64 v[4:5], 15, v[4:5]
	v_lshl_add_u64 v[4:5], v[56:57], 0, v[4:5]
	s_waitcnt vmcnt(0)
	v_mov_b64 v[66:67], v[196:197]
	v_mov_b64 v[68:69], v[198:199]
	v_add_co_u32_e32 v4, vcc, s13, v4
	v_ashrrev_i32_e32 v9, 31, v8
	s_nop 0
	v_addc_co_u32_e32 v5, vcc, 0, v5, vcc
	v_mov_b64 v[70:71], v[200:201]
	v_mov_b64 v[72:73], v[202:203]
	v_lshlrev_b64 v[4:5], 16, v[8:9]
	v_lshl_add_u64 v[12:13], v[52:53], 0, v[4:5]
	v_lshl_add_u64 v[4:5], v[54:55], 0, v[4:5]
	v_mov_b64 v[74:75], v[204:205]
	v_mov_b64 v[76:77], v[206:207]
	v_mov_b64 v[78:79], v[208:209]
	v_mov_b64 v[80:81], v[210:211]
	v_mov_b64 v[52:53], v[212:213]
	v_mov_b64 v[54:55], v[214:215]
	v_mov_b64 v[82:83], v[216:217]
	v_mov_b64 v[84:85], v[218:219]
	s_waitcnt vmcnt(5)
	v_lshlrev_b32_e32 v12, 16, v66
	v_and_b32_e32 v13, 0xffff0000, v66
	v_lshlrev_b32_e32 v66, 16, v67
	v_and_b32_e32 v67, 0xffff0000, v67
	s_waitcnt vmcnt(4)
	v_lshlrev_b32_e32 v4, 16, v70
	v_and_b32_e32 v5, 0xffff0000, v70
	s_waitcnt vmcnt(0)
; #define LAS __attribute__((address_space(3)))
; __device__ __forceinline__ u32x4 pack8(const float* f) { u32x4 w; w.x = cvt_pk_bf16(f[0], f[1]); w.y = cvt_pk_bf16(f[2], f[3]); w.z = cvt_pk_bf16(f[4], f[5]); w.w = cvt_pk_bf16(f[6], f[7]); return w; }
; __device__ __forceinline__ f32x16 mfma32(bf16x8 a, bf16x8 b, f32x16 c) { return __builtin_amdgcn_mfma_f32_32x32x16_bf16(a, b, c, 0, 0, 0); }
; __device__ __forceinline__ f32x16 zero16() { return (f32x16){0.f, 0.f, 0.f, 0.f, 0.f, 0.f, 0.f, 0.f, 0.f, 0.f, 0.f, 0.f, 0.f, 0.f, 0.f, 0.f}; }
; __device__ __forceinline__ void r1_item(const bf16_t* __restrict__ projT, bf16_t* stloc, const float* __restrict__ cosT, const float* __restrict__ sinT, float lgf2, float lgb2, int item, int seqlen, LAS unsigned char* lds) {
;     ...
;         for (int j = 0; j < 8; ++j) { const float cv = j < 4 ? c0[j & 3] : c1[j & 3], sv = j < 4 ? s0[j & 3] : s1[j & 3];
;             const float r1 = (k1[j] * cv - k2[j] * sv) * scale, r2 = (k1[j] * sv + k2[j] * cv) * scale;
;             const int tl = 8 * t8 + j; const float df = __builtin_amdgcn_exp2f((float)(127 - tl) * lgf2), db = __builtin_amdgcn_exp2f((float)tl * lgb2);
;             f1[j] = r1 * df; f2[j] = r2 * df; b1[j] = r1 * db; b2[j] = r2 * db; }
;         *(LAS u32x4*)(KTf + d * KT_STRIDE + 8 * t8) = pack8(f1); *(LAS u32x4*)(KTf + (d + 64) * KT_STRIDE + 8 * t8) = pack8(f2);
;         *(LAS u32x4*)(KTb + d * KT_STRIDE + 8 * t8) = pack8(b1); *(LAS u32x4*)(KTb + (d + 64) * KT_STRIDE + 8 * t8) = pack8(b2);
;     }
;     __syncthreads();
; #pragma unroll
;     for (int dir = 0; dir < 2; ++dir) {
;         LAS bf16_t* KT = dir ? KTb : KTf;
;         bf16_t* dst = stloc + ((size_t)(ch * 4 + h) * 2 + dir) * 32768;
; #pragma unroll
;         for (int ct = 0; ct < 4; ++ct) {
;             f32x16 acc = zero16();
; #pragma unroll
;             for (int s = 0; s < 8; ++s) { const bf16x8 bfr = *(const LAS bf16x8*)(KT + (32 * ct + c) * KT_STRIDE + 16 * s + 8 * hh); acc = mfma32(af[s], bfr, acc); }
	v_pk_mul_f32 v[16:17], v[82:83], v[12:13]
	s_nop 0
	v_pk_fma_f32 v[16:17], v[78:79], v[4:5], v[16:17]
	v_pk_mul_f32 v[4:5], v[82:83], v[4:5]
	v_pk_mul_f32 v[16:17], v[16:17], s[64:65] op_sel_hi:[1,0]
	v_pk_fma_f32 v[4:5], v[78:79], v[12:13], v[4:5] neg_lo:[0,0,1] neg_hi:[0,0,1]
	v_pk_mul_f32 v[56:57], v[60:61], v[16:17]
	v_pk_mul_f32 v[4:5], v[4:5], s[64:65] op_sel_hi:[1,0]
	v_pk_mul_f32 v[16:17], v[58:59], v[16:17]
	v_pk_mul_f32 v[12:13], v[60:61], v[4:5]
	v_lshlrev_b32_e32 v60, 16, v71
	v_and_b32_e32 v61, 0xffff0000, v71
	v_pk_mul_f32 v[70:71], v[84:85], v[66:67]
	v_pk_mul_f32 v[58:59], v[58:59], v[4:5]
	v_pk_fma_f32 v[70:71], v[80:81], v[60:61], v[70:71]
	v_pk_mul_f32 v[60:61], v[84:85], v[60:61]
	v_pk_mul_f32 v[70:71], v[70:71], s[64:65] op_sel_hi:[1,0]
	v_pk_fma_f32 v[60:61], v[80:81], v[66:67], v[60:61] neg_lo:[0,0,1] neg_hi:[0,0,1]
	v_lshlrev_b32_e32 v66, 16, v72
	v_and_b32_e32 v67, 0xffff0000, v72
	v_lshlrev_b32_e32 v80, 16, v68
	v_and_b32_e32 v81, 0xffff0000, v68
	v_pk_mul_f32 v[82:83], v[52:53], v[80:81]
	v_pk_mul_f32 v[52:53], v[52:53], v[66:67]
	v_pk_fma_f32 v[82:83], v[74:75], v[66:67], v[82:83]
	v_pk_fma_f32 v[52:53], v[74:75], v[80:81], v[52:53] neg_lo:[0,0,1] neg_hi:[0,0,1]
	v_pk_mul_f32 v[60:61], v[60:61], s[64:65] op_sel_hi:[1,0]
	v_pk_mul_f32 v[82:83], v[82:83], s[64:65] op_sel_hi:[1,0]
	v_pk_mul_f32 v[52:53], v[52:53], s[64:65] op_sel_hi:[1,0]
	v_pk_mul_f32 v[78:79], v[64:65], v[70:71]
	v_pk_mul_f32 v[64:65], v[64:65], v[60:61]
	v_pk_mul_f32 v[84:85], v[6:7], v[82:83]
	v_pk_mul_f32 v[6:7], v[6:7], v[52:53]
	v_pk_mul_f32 v[66:67], v[10:11], v[82:83]
	v_pk_mul_f32 v[10:11], v[10:11], v[52:53]
	v_pk_mul_f32 v[52:53], v[62:63], v[70:71]
	v_pk_mul_f32 v[60:61], v[62:63], v[60:61]
	v_lshlrev_b32_e32 v62, 16, v69
	v_and_b32_e32 v63, 0xffff0000, v69
	v_lshlrev_b32_e32 v4, 16, v73
	v_and_b32_e32 v5, 0xffff0000, v73
	v_pk_mul_f32 v[68:69], v[54:55], v[62:63]
	s_nop 0
	v_pk_fma_f32 v[68:69], v[76:77], v[4:5], v[68:69]
	v_pk_mul_f32 v[4:5], v[54:55], v[4:5]
	v_pk_mul_f32 v[68:69], v[68:69], s[64:65] op_sel_hi:[1,0]
	v_pk_fma_f32 v[4:5], v[76:77], v[62:63], v[4:5] neg_lo:[0,0,1] neg_hi:[0,0,1]
	v_pk_mul_f32 v[70:71], v[2:3], v[68:69]
	v_pk_mul_f32 v[4:5], v[4:5], s[64:65] op_sel_hi:[1,0]
	s_nop 0
	v_pk_mul_f32 v[54:55], v[2:3], v[4:5]
	v_pk_mul_f32 v[62:63], v[14:15], v[4:5]
	v_cvt_pk_bf16_f32 v2, v12, v13
	v_cvt_pk_bf16_f32 v3, v64, v65
	v_cvt_pk_bf16_f32 v4, v6, v7
	v_cvt_pk_bf16_f32 v5, v54, v55
	v_mad_u64_u32 v[6:7], s[10:11], v8, s12, v[50:51]
	ds_write_b128 v6, v[2:5]
	v_cvt_pk_bf16_f32 v2, v56, v57
	v_cvt_pk_bf16_f32 v3, v78, v79
	v_cvt_pk_bf16_f32 v4, v84, v85
	v_cvt_pk_bf16_f32 v5, v70, v71
	v_pk_mul_f32 v[14:15], v[14:15], v[68:69]
	ds_write_b128 v6, v[2:5] offset:17408
	v_cvt_pk_bf16_f32 v2, v58, v59
	v_cvt_pk_bf16_f32 v3, v60, v61
	v_cvt_pk_bf16_f32 v4, v10, v11
	v_cvt_pk_bf16_f32 v5, v62, v63
	v_add_u32_e32 v54, 0, v0
	ds_write_b128 v6, v[2:5] offset:34816
	v_cvt_pk_bf16_f32 v2, v16, v17
	v_cvt_pk_bf16_f32 v3, v52, v53
	v_cvt_pk_bf16_f32 v4, v66, v67
	v_cvt_pk_bf16_f32 v5, v14, v15
	v_mad_u32_u24 v0, v118, s12, v54
	ds_write_b128 v6, v[2:5] offset:52224
	s_waitcnt lgkmcnt(0)
	s_barrier
	ds_read_b128 v[2:5], v0
	ds_read_b128 v[56:59], v0 offset:32
	ds_read_b128 v[146:149], v0 offset:64
	ds_read_b128 v[150:153], v0 offset:96
	ds_read_b128 v[154:157], v0 offset:128
	ds_read_b128 v[158:161], v0 offset:160
	ds_read_b128 v[162:165], v0 offset:192
	ds_read_b128 v[166:169], v0 offset:224
	s_waitcnt lgkmcnt(7)
	v_mfma_f32_32x32x16_bf16 v[2:17], v[46:49], v[2:5], 0
	v_lshlrev_b32_e32 v50, 9, v51
	v_lshl_or_b32 v60, s43, 7, v50
	v_or_b32_e32 v50, v60, v118
	v_ashrrev_i32_e32 v51, 31, v50
	v_lshl_add_u64 v[116:117], v[50:51], 1, s[6:7]
	v_ashrrev_i32_e32 v51, 31, v60
	v_lshl_add_u64 v[52:53], v[50:51], 1, s[6:7]
	s_waitcnt lgkmcnt(6)
	v_mfma_f32_32x32x16_bf16 v[2:17], v[42:45], v[56:59], v[2:17]
	v_or_b32_e32 v55, 0x800, v60
	v_or_b32_e32 v121, 0xc80, v60
	v_or_b32_e32 v122, 0xd00, v60
	v_or_b32_e32 v123, 0xd80, v60
	v_or_b32_e32 v51, 32, v118
	v_mad_u32_u24 v120, v51, s12, v54
	s_waitcnt lgkmcnt(5)
	v_mfma_f32_32x32x16_bf16 v[2:17], v[38:41], v[146:149], v[2:17]
	s_waitcnt lgkmcnt(4)
	v_mfma_f32_32x32x16_bf16 v[2:17], v[34:37], v[150:153], v[2:17]
	s_waitcnt lgkmcnt(3)
	v_mfma_f32_32x32x16_bf16 v[2:17], v[30:33], v[154:157], v[2:17]
	s_waitcnt lgkmcnt(2)
	v_mfma_f32_32x32x16_bf16 v[2:17], v[26:29], v[158:161], v[2:17]
	s_waitcnt lgkmcnt(1)
	v_mfma_f32_32x32x16_bf16 v[2:17], v[22:25], v[162:165], v[2:17]
	s_waitcnt lgkmcnt(0)
; #define LAS __attribute__((address_space(3)))
; __device__ __forceinline__ unsigned cvt_pk_bf16(float lo, float hi) { const f32v2_t v = {lo, hi}; const bf16v2_t r = __builtin_convertvector(v, bf16v2_t); return __builtin_bit_cast(unsigned, r); }
; __device__ __forceinline__ f32x16 mfma32(bf16x8 a, bf16x8 b, f32x16 c) { return __builtin_amdgcn_mfma_f32_32x32x16_bf16(a, b, c, 0, 0, 0); }
; __device__ __forceinline__ f32x16 zero16() { return (f32x16){0.f, 0.f, 0.f, 0.f, 0.f, 0.f, 0.f, 0.f, 0.f, 0.f, 0.f, 0.f, 0.f, 0.f, 0.f, 0.f}; }
; __device__ __forceinline__ void r1_item(const bf16_t* __restrict__ projT, bf16_t* stloc, const float* __restrict__ cosT, const float* __restrict__ sinT, float lgf2, float lgb2, int item, int seqlen, LAS unsigned char* lds) {
;     ...
;     for (int dir = 0; dir < 2; ++dir) {
;         LAS bf16_t* KT = dir ? KTb : KTf;
;         bf16_t* dst = stloc + ((size_t)(ch * 4 + h) * 2 + dir) * 32768;
; #pragma unroll
;         for (int ct = 0; ct < 4; ++ct) {
;             f32x16 acc = zero16();
; #pragma unroll
;             for (int s = 0; s < 8; ++s) { const bf16x8 bfr = *(const LAS bf16x8*)(KT + (32 * ct + c) * KT_STRIDE + 16 * s + 8 * hh); acc = mfma32(af[s], bfr, acc); }
; #pragma unroll
;             for (int rg = 0; rg < 16; ++rg) { const int dv = 32 * w + (rg & 3) + 8 * (rg >> 2) + 4 * hh; dst[dv * 128 + 32 * ct + c] = (bf16_t)(cvt_pk_bf16(acc[rg], 0.f) & 0xffffu); }
;         }
;     }
	v_mfma_f32_32x32x16_bf16 v[2:17], v[18:21], v[166:169], v[2:17]
	v_or_b32_e32 v56, 0x880, v60
	v_or_b32_e32 v57, 0x900, v60
	v_or_b32_e32 v58, 0x980, v60
	v_or_b32_e32 v59, 0xc00, v60
	s_nop 7
	v_cvt_pk_bf16_f32 v2, v2, s0
	global_store_short v[116:117], v2, off
	v_cvt_pk_bf16_f32 v2, v3, s0
	global_store_short v[52:53], v2, off offset:256
	v_cvt_pk_bf16_f32 v2, v4, s0
	global_store_short v[52:53], v2, off offset:512
	v_cvt_pk_bf16_f32 v2, v5, s0
	global_store_short v[52:53], v2, off offset:768
	v_cvt_pk_bf16_f32 v2, v6, s0
	global_store_short v[52:53], v2, off offset:2048
	v_cvt_pk_bf16_f32 v2, v7, s0
	global_store_short v[52:53], v2, off offset:2304
	v_cvt_pk_bf16_f32 v2, v8, s0
	global_store_short v[52:53], v2, off offset:2560
	v_cvt_pk_bf16_f32 v2, v9, s0
	global_store_short v[52:53], v2, off offset:2816
	v_or_b32_e32 v2, v55, v118
	v_ashrrev_i32_e32 v3, 31, v2
	v_lshl_add_u64 v[100:101], v[2:3], 1, s[6:7]
	v_or_b32_e32 v2, v56, v118
	v_ashrrev_i32_e32 v3, 31, v2
	v_lshl_add_u64 v[102:103], v[2:3], 1, s[6:7]
	v_or_b32_e32 v2, v57, v118
	v_ashrrev_i32_e32 v3, 31, v2
	v_lshl_add_u64 v[104:105], v[2:3], 1, s[6:7]
	v_or_b32_e32 v2, v58, v118
	v_ashrrev_i32_e32 v3, 31, v2
	v_lshl_add_u64 v[106:107], v[2:3], 1, s[6:7]
	v_or_b32_e32 v2, v59, v118
	v_cvt_pk_bf16_f32 v4, v10, s0
	v_ashrrev_i32_e32 v3, 31, v2
	global_store_short v[100:101], v4, off
	v_cvt_pk_bf16_f32 v4, v11, s0
	v_lshl_add_u64 v[108:109], v[2:3], 1, s[6:7]
	v_or_b32_e32 v2, v121, v118
	global_store_short v[102:103], v4, off
	v_cvt_pk_bf16_f32 v4, v12, s0
	v_ashrrev_i32_e32 v3, 31, v2
	global_store_short v[104:105], v4, off
	v_cvt_pk_bf16_f32 v4, v13, s0
	v_lshl_add_u64 v[110:111], v[2:3], 1, s[6:7]
	v_or_b32_e32 v2, v122, v118
	global_store_short v[106:107], v4, off
	v_cvt_pk_bf16_f32 v4, v14, s0
	v_ashrrev_i32_e32 v3, 31, v2
	global_store_short v[108:109], v4, off
	v_cvt_pk_bf16_f32 v4, v15, s0
	v_lshl_add_u64 v[112:113], v[2:3], 1, s[6:7]
	v_or_b32_e32 v2, v123, v118
	global_store_short v[110:111], v4, off
	v_cvt_pk_bf16_f32 v4, v16, s0
	v_ashrrev_i32_e32 v3, 31, v2
	global_store_short v[112:113], v4, off
	v_cvt_pk_bf16_f32 v4, v17, s0
	v_lshl_add_u64 v[114:115], v[2:3], 1, s[6:7]
	global_store_short v[114:115], v4, off
	ds_read_b128 v[2:5], v120
	ds_read_b128 v[60:63], v120 offset:32
	ds_read_b128 v[146:149], v120 offset:64
	ds_read_b128 v[150:153], v120 offset:96
	ds_read_b128 v[154:157], v120 offset:128
	ds_read_b128 v[158:161], v120 offset:160
	ds_read_b128 v[162:165], v120 offset:192
	ds_read_b128 v[166:169], v120 offset:224
	s_waitcnt lgkmcnt(7)
	v_mfma_f32_32x32x16_bf16 v[2:17], v[46:49], v[2:5], 0
	v_add_co_u32_e32 v116, vcc, s26, v116
	s_nop 1
	v_addc_co_u32_e32 v117, vcc, 0, v117, vcc
	s_waitcnt lgkmcnt(6)
	v_mfma_f32_32x32x16_bf16 v[2:17], v[42:45], v[60:63], v[2:17]
	s_waitcnt lgkmcnt(5)
	v_mfma_f32_32x32x16_bf16 v[2:17], v[38:41], v[146:149], v[2:17]
	s_waitcnt lgkmcnt(4)
	v_mfma_f32_32x32x16_bf16 v[2:17], v[34:37], v[150:153], v[2:17]
	s_waitcnt lgkmcnt(3)
	v_mfma_f32_32x32x16_bf16 v[2:17], v[30:33], v[154:157], v[2:17]
	s_waitcnt lgkmcnt(2)
	v_mfma_f32_32x32x16_bf16 v[2:17], v[26:29], v[158:161], v[2:17]
	s_waitcnt lgkmcnt(1)
	v_mfma_f32_32x32x16_bf16 v[2:17], v[22:25], v[162:165], v[2:17]
	s_waitcnt lgkmcnt(0)
	v_mfma_f32_32x32x16_bf16 v[2:17], v[18:21], v[166:169], v[2:17]
	s_nop 11
	v_cvt_pk_bf16_f32 v2, v2, s0
	global_store_short v[52:53], v2, off offset:64
	v_cvt_pk_bf16_f32 v2, v3, s0
	global_store_short v[52:53], v2, off offset:320
	v_cvt_pk_bf16_f32 v2, v4, s0
	global_store_short v[52:53], v2, off offset:576
	v_cvt_pk_bf16_f32 v2, v5, s0
	global_store_short v[52:53], v2, off offset:832
	v_cvt_pk_bf16_f32 v2, v6, s0
	global_store_short v[52:53], v2, off offset:2112
	v_cvt_pk_bf16_f32 v2, v7, s0
	global_store_short v[52:53], v2, off offset:2368
	v_cvt_pk_bf16_f32 v2, v8, s0
	global_store_short v[52:53], v2, off offset:2624
	v_cvt_pk_bf16_f32 v2, v9, s0
	global_store_short v[52:53], v2, off offset:2880
	v_or_b32_e32 v2, v55, v51
	v_ashrrev_i32_e32 v3, 31, v2
	v_lshl_add_u64 v[84:85], v[2:3], 1, s[6:7]
	v_or_b32_e32 v2, v56, v51
	v_ashrrev_i32_e32 v3, 31, v2
	v_lshl_add_u64 v[86:87], v[2:3], 1, s[6:7]
	v_or_b32_e32 v2, v57, v51
	v_ashrrev_i32_e32 v3, 31, v2
	v_lshl_add_u64 v[88:89], v[2:3], 1, s[6:7]
	v_or_b32_e32 v2, v58, v51
	v_ashrrev_i32_e32 v3, 31, v2
	v_lshl_add_u64 v[90:91], v[2:3], 1, s[6:7]
	v_or_b32_e32 v2, v59, v51
	v_cvt_pk_bf16_f32 v4, v10, s0
	v_ashrrev_i32_e32 v3, 31, v2
	global_store_short v[84:85], v4, off
	v_cvt_pk_bf16_f32 v4, v11, s0
	v_lshl_add_u64 v[92:93], v[2:3], 1, s[6:7]
	v_or_b32_e32 v2, v121, v51
	global_store_short v[86:87], v4, off
	v_cvt_pk_bf16_f32 v4, v12, s0
	v_ashrrev_i32_e32 v3, 31, v2
	global_store_short v[88:89], v4, off
	v_cvt_pk_bf16_f32 v4, v13, s0
	v_lshl_add_u64 v[94:95], v[2:3], 1, s[6:7]
	v_or_b32_e32 v2, v122, v51
	global_store_short v[90:91], v4, off
	v_cvt_pk_bf16_f32 v4, v14, s0
	v_ashrrev_i32_e32 v3, 31, v2
	global_store_short v[92:93], v4, off
	v_cvt_pk_bf16_f32 v4, v15, s0
	v_lshl_add_u64 v[96:97], v[2:3], 1, s[6:7]
	v_or_b32_e32 v2, v123, v51
	global_store_short v[94:95], v4, off
	v_cvt_pk_bf16_f32 v4, v16, s0
	v_ashrrev_i32_e32 v3, 31, v2
	global_store_short v[96:97], v4, off
	v_cvt_pk_bf16_f32 v4, v17, s0
	v_lshl_add_u64 v[98:99], v[2:3], 1, s[6:7]
	v_or_b32_e32 v51, 64, v118
	global_store_short v[98:99], v4, off
	v_mad_u32_u24 v119, v51, s12, v54
	ds_read_b128 v[2:5], v119
	ds_read_b128 v[60:63], v119 offset:32
	ds_read_b128 v[146:149], v119 offset:64
	ds_read_b128 v[150:153], v119 offset:96
	ds_read_b128 v[154:157], v119 offset:128
	ds_read_b128 v[158:161], v119 offset:160
	ds_read_b128 v[162:165], v119 offset:192
	ds_read_b128 v[166:169], v119 offset:224
	s_waitcnt lgkmcnt(7)
; #define LAS __attribute__((address_space(3)))
; __device__ __forceinline__ unsigned cvt_pk_bf16(float lo, float hi) { const f32v2_t v = {lo, hi}; const bf16v2_t r = __builtin_convertvector(v, bf16v2_t); return __builtin_bit_cast(unsigned, r); }
; __device__ __forceinline__ f32x16 mfma32(bf16x8 a, bf16x8 b, f32x16 c) { return __builtin_amdgcn_mfma_f32_32x32x16_bf16(a, b, c, 0, 0, 0); }
; __device__ __forceinline__ f32x16 zero16() { return (f32x16){0.f, 0.f, 0.f, 0.f, 0.f, 0.f, 0.f, 0.f, 0.f, 0.f, 0.f, 0.f, 0.f, 0.f, 0.f, 0.f}; }
; __device__ __forceinline__ void r1_item(const bf16_t* __restrict__ projT, bf16_t* stloc, const float* __restrict__ cosT, const float* __restrict__ sinT, float lgf2, float lgb2, int item, int seqlen, LAS unsigned char* lds) {
;     ...
;     for (int dir = 0; dir < 2; ++dir) {
;         LAS bf16_t* KT = dir ? KTb : KTf;
;         bf16_t* dst = stloc + ((size_t)(ch * 4 + h) * 2 + dir) * 32768;
; #pragma unroll
;         for (int ct = 0; ct < 4; ++ct) {
;             f32x16 acc = zero16();
; #pragma unroll
;             for (int s = 0; s < 8; ++s) { const bf16x8 bfr = *(const LAS bf16x8*)(KT + (32 * ct + c) * KT_STRIDE + 16 * s + 8 * hh); acc = mfma32(af[s], bfr, acc); }
; #pragma unroll
;             for (int rg = 0; rg < 16; ++rg) { const int dv = 32 * w + (rg & 3) + 8 * (rg >> 2) + 4 * hh; dst[dv * 128 + 32 * ct + c] = (bf16_t)(cvt_pk_bf16(acc[rg], 0.f) & 0xffffu); }
;         }
;     }
	v_mfma_f32_32x32x16_bf16 v[2:17], v[46:49], v[2:5], 0
	v_or_b32_e32 v118, 0x60, v118
	s_waitcnt lgkmcnt(6)
	v_mfma_f32_32x32x16_bf16 v[2:17], v[42:45], v[60:63], v[2:17]
	s_waitcnt lgkmcnt(5)
	v_mfma_f32_32x32x16_bf16 v[2:17], v[38:41], v[146:149], v[2:17]
	s_waitcnt lgkmcnt(4)
	v_mfma_f32_32x32x16_bf16 v[2:17], v[34:37], v[150:153], v[2:17]
	s_waitcnt lgkmcnt(3)
	v_mfma_f32_32x32x16_bf16 v[2:17], v[30:33], v[154:157], v[2:17]
	s_waitcnt lgkmcnt(2)
	v_mfma_f32_32x32x16_bf16 v[2:17], v[26:29], v[158:161], v[2:17]
	s_waitcnt lgkmcnt(1)
	v_mfma_f32_32x32x16_bf16 v[2:17], v[22:25], v[162:165], v[2:17]
	s_waitcnt lgkmcnt(0)
	v_mfma_f32_32x32x16_bf16 v[2:17], v[18:21], v[166:169], v[2:17]
	s_nop 11
	v_cvt_pk_bf16_f32 v2, v2, s0
	global_store_short v[52:53], v2, off offset:128
	v_cvt_pk_bf16_f32 v2, v3, s0
	global_store_short v[52:53], v2, off offset:384
	v_cvt_pk_bf16_f32 v2, v4, s0
	global_store_short v[52:53], v2, off offset:640
	v_cvt_pk_bf16_f32 v2, v5, s0
	global_store_short v[52:53], v2, off offset:896
	v_cvt_pk_bf16_f32 v2, v6, s0
	global_store_short v[52:53], v2, off offset:2176
	v_cvt_pk_bf16_f32 v2, v7, s0
	global_store_short v[52:53], v2, off offset:2432
	v_cvt_pk_bf16_f32 v2, v8, s0
	global_store_short v[52:53], v2, off offset:2688
	v_cvt_pk_bf16_f32 v2, v9, s0
	global_store_short v[52:53], v2, off offset:2944
	v_or_b32_e32 v2, v55, v51
	v_ashrrev_i32_e32 v3, 31, v2
	v_lshl_add_u64 v[68:69], v[2:3], 1, s[6:7]
	v_or_b32_e32 v2, v56, v51
	v_ashrrev_i32_e32 v3, 31, v2
	v_lshl_add_u64 v[70:71], v[2:3], 1, s[6:7]
	v_or_b32_e32 v2, v57, v51
	v_ashrrev_i32_e32 v3, 31, v2
	v_lshl_add_u64 v[72:73], v[2:3], 1, s[6:7]
	v_or_b32_e32 v2, v58, v51
	v_ashrrev_i32_e32 v3, 31, v2
	v_lshl_add_u64 v[74:75], v[2:3], 1, s[6:7]
	v_or_b32_e32 v2, v59, v51
	v_cvt_pk_bf16_f32 v4, v10, s0
	v_ashrrev_i32_e32 v3, 31, v2
	global_store_short v[68:69], v4, off
	v_cvt_pk_bf16_f32 v4, v11, s0
	v_lshl_add_u64 v[76:77], v[2:3], 1, s[6:7]
	v_or_b32_e32 v2, v121, v51
	global_store_short v[70:71], v4, off
	v_cvt_pk_bf16_f32 v4, v12, s0
	v_ashrrev_i32_e32 v3, 31, v2
	global_store_short v[72:73], v4, off
	v_cvt_pk_bf16_f32 v4, v13, s0
	v_lshl_add_u64 v[78:79], v[2:3], 1, s[6:7]
	v_or_b32_e32 v2, v122, v51
	global_store_short v[74:75], v4, off
	v_cvt_pk_bf16_f32 v4, v14, s0
	v_ashrrev_i32_e32 v3, 31, v2
	global_store_short v[76:77], v4, off
	v_cvt_pk_bf16_f32 v4, v15, s0
	v_lshl_add_u64 v[80:81], v[2:3], 1, s[6:7]
	v_or_b32_e32 v2, v123, v51
	global_store_short v[78:79], v4, off
	v_cvt_pk_bf16_f32 v4, v16, s0
	v_ashrrev_i32_e32 v3, 31, v2
	global_store_short v[80:81], v4, off
	v_cvt_pk_bf16_f32 v4, v17, s0
	v_lshl_add_u64 v[82:83], v[2:3], 1, s[6:7]
	global_store_short v[82:83], v4, off
	v_mad_u32_u24 v51, v118, s12, v54
	ds_read_b128 v[2:5], v51
	ds_read_b128 v[60:63], v51 offset:32
	ds_read_b128 v[146:149], v51 offset:64
	ds_read_b128 v[150:153], v51 offset:96
	ds_read_b128 v[154:157], v51 offset:128
	ds_read_b128 v[158:161], v51 offset:160
	ds_read_b128 v[162:165], v51 offset:192
	ds_read_b128 v[166:169], v51 offset:224
	s_waitcnt lgkmcnt(7)
	v_mfma_f32_32x32x16_bf16 v[2:17], v[46:49], v[2:5], 0
	s_waitcnt lgkmcnt(6)
	v_mfma_f32_32x32x16_bf16 v[2:17], v[42:45], v[60:63], v[2:17]
	s_waitcnt lgkmcnt(5)
	v_mfma_f32_32x32x16_bf16 v[2:17], v[38:41], v[146:149], v[2:17]
	s_waitcnt lgkmcnt(4)
	v_mfma_f32_32x32x16_bf16 v[2:17], v[34:37], v[150:153], v[2:17]
	s_waitcnt lgkmcnt(3)
	v_mfma_f32_32x32x16_bf16 v[2:17], v[30:33], v[154:157], v[2:17]
	s_waitcnt lgkmcnt(2)
	v_mfma_f32_32x32x16_bf16 v[2:17], v[26:29], v[158:161], v[2:17]
	s_waitcnt lgkmcnt(1)
	v_mfma_f32_32x32x16_bf16 v[2:17], v[22:25], v[162:165], v[2:17]
	s_waitcnt lgkmcnt(0)
	v_mfma_f32_32x32x16_bf16 v[2:17], v[18:21], v[166:169], v[2:17]
	s_nop 11
	v_cvt_pk_bf16_f32 v2, v2, s0
	global_store_short v[52:53], v2, off offset:192
	v_cvt_pk_bf16_f32 v2, v3, s0
	global_store_short v[52:53], v2, off offset:448
	v_cvt_pk_bf16_f32 v2, v4, s0
	global_store_short v[52:53], v2, off offset:704
	v_cvt_pk_bf16_f32 v2, v5, s0
	global_store_short v[52:53], v2, off offset:960
	v_cvt_pk_bf16_f32 v2, v6, s0
	global_store_short v[52:53], v2, off offset:2240
	v_cvt_pk_bf16_f32 v2, v7, s0
	global_store_short v[52:53], v2, off offset:2496
	v_cvt_pk_bf16_f32 v2, v8, s0
	global_store_short v[52:53], v2, off offset:2752
	v_cvt_pk_bf16_f32 v2, v9, s0
	global_store_short v[52:53], v2, off offset:3008
	v_or_b32_e32 v2, v55, v118
	v_ashrrev_i32_e32 v3, 31, v2
	v_lshl_add_u64 v[66:67], v[2:3], 1, s[6:7]
	v_or_b32_e32 v2, v56, v118
	v_ashrrev_i32_e32 v3, 31, v2
	v_lshl_add_u64 v[64:65], v[2:3], 1, s[6:7]
	v_or_b32_e32 v2, v57, v118
	v_ashrrev_i32_e32 v3, 31, v2
	v_lshl_add_u64 v[62:63], v[2:3], 1, s[6:7]
	v_or_b32_e32 v2, v58, v118
	v_ashrrev_i32_e32 v3, 31, v2
	v_lshl_add_u64 v[60:61], v[2:3], 1, s[6:7]
	v_or_b32_e32 v2, v59, v118
	v_cvt_pk_bf16_f32 v4, v10, s0
	v_ashrrev_i32_e32 v3, 31, v2
	global_store_short v[66:67], v4, off
	v_cvt_pk_bf16_f32 v4, v11, s0
	v_lshl_add_u64 v[58:59], v[2:3], 1, s[6:7]
	v_or_b32_e32 v2, v121, v118
	global_store_short v[64:65], v4, off
	v_cvt_pk_bf16_f32 v4, v12, s0
	v_ashrrev_i32_e32 v3, 31, v2
	global_store_short v[62:63], v4, off
	v_cvt_pk_bf16_f32 v4, v13, s0
	v_lshl_add_u64 v[56:57], v[2:3], 1, s[6:7]
	v_or_b32_e32 v2, v122, v118
	global_store_short v[60:61], v4, off
	v_cvt_pk_bf16_f32 v4, v14, s0
	v_ashrrev_i32_e32 v3, 31, v2
	global_store_short v[58:59], v4, off
	v_cvt_pk_bf16_f32 v4, v15, s0
	v_lshl_add_u64 v[54:55], v[2:3], 1, s[6:7]
	v_or_b32_e32 v2, v123, v118
	global_store_short v[56:57], v4, off
	v_cvt_pk_bf16_f32 v4, v16, s0
	v_ashrrev_i32_e32 v3, 31, v2
	global_store_short v[54:55], v4, off
	v_cvt_pk_bf16_f32 v4, v17, s0
	v_lshl_add_u64 v[52:53], v[2:3], 1, s[6:7]
	global_store_short v[52:53], v4, off
	ds_read_b128 v[2:5], v0 offset:34816
	ds_read_b128 v[122:125], v0 offset:34848
	ds_read_b128 v[146:149], v0 offset:34880
	ds_read_b128 v[150:153], v0 offset:34912
	ds_read_b128 v[154:157], v0 offset:34944
	ds_read_b128 v[158:161], v0 offset:34976
	ds_read_b128 v[162:165], v0 offset:35008
	ds_read_b128 v[166:169], v0 offset:35040
	s_waitcnt lgkmcnt(7)
; #define LAS __attribute__((address_space(3)))
; __device__ __forceinline__ unsigned cvt_pk_bf16(float lo, float hi) { const f32v2_t v = {lo, hi}; const bf16v2_t r = __builtin_convertvector(v, bf16v2_t); return __builtin_bit_cast(unsigned, r); }
; __device__ __forceinline__ f32x16 mfma32(bf16x8 a, bf16x8 b, f32x16 c) { return __builtin_amdgcn_mfma_f32_32x32x16_bf16(a, b, c, 0, 0, 0); }
; __device__ __forceinline__ f32x16 zero16() { return (f32x16){0.f, 0.f, 0.f, 0.f, 0.f, 0.f, 0.f, 0.f, 0.f, 0.f, 0.f, 0.f, 0.f, 0.f, 0.f, 0.f}; }
; __device__ __forceinline__ void r1_item(const bf16_t* __restrict__ projT, bf16_t* stloc, const float* __restrict__ cosT, const float* __restrict__ sinT, float lgf2, float lgb2, int item, int seqlen, LAS unsigned char* lds) {
;     ...
;     for (int dir = 0; dir < 2; ++dir) {
;         LAS bf16_t* KT = dir ? KTb : KTf;
;         bf16_t* dst = stloc + ((size_t)(ch * 4 + h) * 2 + dir) * 32768;
; #pragma unroll
;         for (int ct = 0; ct < 4; ++ct) {
;             f32x16 acc = zero16();
; #pragma unroll
;             for (int s = 0; s < 8; ++s) { const bf16x8 bfr = *(const LAS bf16x8*)(KT + (32 * ct + c) * KT_STRIDE + 16 * s + 8 * hh); acc = mfma32(af[s], bfr, acc); }
; #pragma unroll
;             for (int rg = 0; rg < 16; ++rg) { const int dv = 32 * w + (rg & 3) + 8 * (rg >> 2) + 4 * hh; dst[dv * 128 + 32 * ct + c] = (bf16_t)(cvt_pk_bf16(acc[rg], 0.f) & 0xffffu); }
;         }
;     }
	v_mfma_f32_32x32x16_bf16 v[2:17], v[46:49], v[2:5], 0
	s_waitcnt lgkmcnt(6)
	v_mfma_f32_32x32x16_bf16 v[2:17], v[42:45], v[122:125], v[2:17]
	s_waitcnt lgkmcnt(5)
	v_mfma_f32_32x32x16_bf16 v[2:17], v[38:41], v[146:149], v[2:17]
	s_waitcnt lgkmcnt(4)
	v_mfma_f32_32x32x16_bf16 v[2:17], v[34:37], v[150:153], v[2:17]
	s_waitcnt lgkmcnt(3)
	v_mfma_f32_32x32x16_bf16 v[2:17], v[30:33], v[154:157], v[2:17]
	s_waitcnt lgkmcnt(2)
	v_mfma_f32_32x32x16_bf16 v[2:17], v[26:29], v[158:161], v[2:17]
	s_waitcnt lgkmcnt(1)
	v_mfma_f32_32x32x16_bf16 v[2:17], v[22:25], v[162:165], v[2:17]
	s_waitcnt lgkmcnt(0)
	v_mfma_f32_32x32x16_bf16 v[2:17], v[18:21], v[166:169], v[2:17]
	s_nop 11
	v_cvt_pk_bf16_f32 v0, v2, s0
	v_or_b32_e32 v2, 0x80, v50
	global_store_short v[116:117], v0, off
	v_cvt_pk_bf16_f32 v0, v3, s0
	v_ashrrev_i32_e32 v3, 31, v2
	v_lshl_add_u64 v[2:3], v[2:3], 1, s[6:7]
	v_add_co_u32_e32 v2, vcc, s26, v2
	s_nop 1
	v_addc_co_u32_e32 v3, vcc, 0, v3, vcc
	global_store_short v[2:3], v0, off
	v_or_b32_e32 v2, 0x100, v50
	v_ashrrev_i32_e32 v3, 31, v2
	v_lshl_add_u64 v[2:3], v[2:3], 1, s[6:7]
	v_add_co_u32_e32 v2, vcc, s26, v2
	v_cvt_pk_bf16_f32 v0, v4, s0
	s_nop 0
	v_addc_co_u32_e32 v3, vcc, 0, v3, vcc
	global_store_short v[2:3], v0, off
	v_or_b32_e32 v2, 0x180, v50
	v_ashrrev_i32_e32 v3, 31, v2
	v_lshl_add_u64 v[2:3], v[2:3], 1, s[6:7]
	v_add_co_u32_e32 v2, vcc, s26, v2
	v_cvt_pk_bf16_f32 v0, v5, s0
	s_nop 0
	v_addc_co_u32_e32 v3, vcc, 0, v3, vcc
	global_store_short v[2:3], v0, off
	v_or_b32_e32 v2, 0x400, v50
	v_ashrrev_i32_e32 v3, 31, v2
	v_lshl_add_u64 v[2:3], v[2:3], 1, s[6:7]
	v_add_co_u32_e32 v2, vcc, s26, v2
	v_cvt_pk_bf16_f32 v0, v6, s0
	s_nop 0
	v_addc_co_u32_e32 v3, vcc, 0, v3, vcc
	global_store_short v[2:3], v0, off
	v_or_b32_e32 v2, 0x480, v50
	v_ashrrev_i32_e32 v3, 31, v2
	v_lshl_add_u64 v[2:3], v[2:3], 1, s[6:7]
	v_add_co_u32_e32 v2, vcc, s26, v2
	v_cvt_pk_bf16_f32 v0, v7, s0
	s_nop 0
	v_addc_co_u32_e32 v3, vcc, 0, v3, vcc
	global_store_short v[2:3], v0, off
	v_or_b32_e32 v2, 0x500, v50
	v_ashrrev_i32_e32 v3, 31, v2
	v_lshl_add_u64 v[2:3], v[2:3], 1, s[6:7]
	v_add_co_u32_e32 v2, vcc, s26, v2
	v_cvt_pk_bf16_f32 v0, v8, s0
	s_nop 0
	v_addc_co_u32_e32 v3, vcc, 0, v3, vcc
	global_store_short v[2:3], v0, off
	v_or_b32_e32 v2, 0x580, v50
	v_ashrrev_i32_e32 v3, 31, v2
	v_lshl_add_u64 v[2:3], v[2:3], 1, s[6:7]
	v_add_co_u32_e32 v2, vcc, s26, v2
	v_cvt_pk_bf16_f32 v0, v9, s0
	s_nop 0
	v_addc_co_u32_e32 v3, vcc, 0, v3, vcc
	global_store_short v[2:3], v0, off
	v_add_co_u32_e32 v2, vcc, s26, v100
	v_cvt_pk_bf16_f32 v0, v10, s0
	s_nop 0
	v_addc_co_u32_e32 v3, vcc, 0, v101, vcc
	global_store_short v[2:3], v0, off
	v_add_co_u32_e32 v2, vcc, s26, v102
	v_cvt_pk_bf16_f32 v0, v11, s0
	s_nop 0
	v_addc_co_u32_e32 v3, vcc, 0, v103, vcc
	global_store_short v[2:3], v0, off
	v_add_co_u32_e32 v2, vcc, s26, v104
	v_cvt_pk_bf16_f32 v0, v12, s0
	s_nop 0
	v_addc_co_u32_e32 v3, vcc, 0, v105, vcc
	global_store_short v[2:3], v0, off
	v_add_co_u32_e32 v2, vcc, s26, v106
	v_cvt_pk_bf16_f32 v0, v13, s0
	s_nop 0
	v_addc_co_u32_e32 v3, vcc, 0, v107, vcc
	global_store_short v[2:3], v0, off
	v_add_co_u32_e32 v2, vcc, s26, v108
	v_cvt_pk_bf16_f32 v0, v14, s0
	s_nop 0
	v_addc_co_u32_e32 v3, vcc, 0, v109, vcc
	global_store_short v[2:3], v0, off
	v_add_co_u32_e32 v2, vcc, s26, v110
	v_cvt_pk_bf16_f32 v0, v15, s0
	s_nop 0
	v_addc_co_u32_e32 v3, vcc, 0, v111, vcc
	global_store_short v[2:3], v0, off
	v_add_co_u32_e32 v2, vcc, s26, v112
	v_cvt_pk_bf16_f32 v0, v16, s0
	s_nop 0
	v_addc_co_u32_e32 v3, vcc, 0, v113, vcc
	global_store_short v[2:3], v0, off
	v_add_co_u32_e32 v2, vcc, s26, v114
	v_cvt_pk_bf16_f32 v0, v17, s0
	s_nop 0
	v_addc_co_u32_e32 v3, vcc, 0, v115, vcc
	global_store_short v[2:3], v0, off
	ds_read_b128 v[2:5], v120 offset:34816
	ds_read_b128 v[100:103], v120 offset:34848
	ds_read_b128 v[146:149], v120 offset:34880
	ds_read_b128 v[150:153], v120 offset:34912
	ds_read_b128 v[154:157], v120 offset:34944
	ds_read_b128 v[158:161], v120 offset:34976
	ds_read_b128 v[162:165], v120 offset:35008
	ds_read_b128 v[166:169], v120 offset:35040
	s_waitcnt lgkmcnt(7)
	v_mfma_f32_32x32x16_bf16 v[2:17], v[46:49], v[2:5], 0
	s_waitcnt lgkmcnt(6)
	v_mfma_f32_32x32x16_bf16 v[2:17], v[42:45], v[100:103], v[2:17]
	s_waitcnt lgkmcnt(5)
	v_mfma_f32_32x32x16_bf16 v[2:17], v[38:41], v[146:149], v[2:17]
	s_waitcnt lgkmcnt(4)
	v_mfma_f32_32x32x16_bf16 v[2:17], v[34:37], v[150:153], v[2:17]
	s_waitcnt lgkmcnt(3)
	v_mfma_f32_32x32x16_bf16 v[2:17], v[30:33], v[154:157], v[2:17]
	s_waitcnt lgkmcnt(2)
	v_mfma_f32_32x32x16_bf16 v[2:17], v[26:29], v[158:161], v[2:17]
	s_waitcnt lgkmcnt(1)
	v_mfma_f32_32x32x16_bf16 v[2:17], v[22:25], v[162:165], v[2:17]
	s_waitcnt lgkmcnt(0)
; #define LAS __attribute__((address_space(3)))
; __device__ __forceinline__ unsigned cvt_pk_bf16(float lo, float hi) { const f32v2_t v = {lo, hi}; const bf16v2_t r = __builtin_convertvector(v, bf16v2_t); return __builtin_bit_cast(unsigned, r); }
; __device__ __forceinline__ f32x16 mfma32(bf16x8 a, bf16x8 b, f32x16 c) { return __builtin_amdgcn_mfma_f32_32x32x16_bf16(a, b, c, 0, 0, 0); }
; __device__ __forceinline__ f32x16 zero16() { return (f32x16){0.f, 0.f, 0.f, 0.f, 0.f, 0.f, 0.f, 0.f, 0.f, 0.f, 0.f, 0.f, 0.f, 0.f, 0.f, 0.f}; }
; __device__ __forceinline__ void r1_item(const bf16_t* __restrict__ projT, bf16_t* stloc, const float* __restrict__ cosT, const float* __restrict__ sinT, float lgf2, float lgb2, int item, int seqlen, LAS unsigned char* lds) {
;     ...
;     for (int dir = 0; dir < 2; ++dir) {
;         LAS bf16_t* KT = dir ? KTb : KTf;
;         bf16_t* dst = stloc + ((size_t)(ch * 4 + h) * 2 + dir) * 32768;
; #pragma unroll
;         for (int ct = 0; ct < 4; ++ct) {
;             f32x16 acc = zero16();
; #pragma unroll
;             for (int s = 0; s < 8; ++s) { const bf16x8 bfr = *(const LAS bf16x8*)(KT + (32 * ct + c) * KT_STRIDE + 16 * s + 8 * hh); acc = mfma32(af[s], bfr, acc); }
; #pragma unroll
;             for (int rg = 0; rg < 16; ++rg) { const int dv = 32 * w + (rg & 3) + 8 * (rg >> 2) + 4 * hh; dst[dv * 128 + 32 * ct + c] = (bf16_t)(cvt_pk_bf16(acc[rg], 0.f) & 0xffffu); }
;         }
;     }
	v_mfma_f32_32x32x16_bf16 v[2:17], v[18:21], v[166:169], v[2:17]
	v_or_b32_e32 v100, 32, v50
	v_ashrrev_i32_e32 v101, 31, v100
	v_lshl_add_u64 v[100:101], v[100:101], 1, s[6:7]
	v_add_co_u32_e32 v100, vcc, s26, v100
	s_nop 1
	v_addc_co_u32_e32 v101, vcc, 0, v101, vcc
	s_nop 4
	v_cvt_pk_bf16_f32 v0, v2, s0
	v_or_b32_e32 v2, 0xa0, v50
	global_store_short v[100:101], v0, off
	v_cvt_pk_bf16_f32 v0, v3, s0
	v_ashrrev_i32_e32 v3, 31, v2
	v_lshl_add_u64 v[2:3], v[2:3], 1, s[6:7]
	v_add_co_u32_e32 v2, vcc, s26, v2
	s_nop 1
	v_addc_co_u32_e32 v3, vcc, 0, v3, vcc
	global_store_short v[2:3], v0, off
	v_or_b32_e32 v2, 0x120, v50
	v_ashrrev_i32_e32 v3, 31, v2
	v_lshl_add_u64 v[2:3], v[2:3], 1, s[6:7]
	v_add_co_u32_e32 v2, vcc, s26, v2
	v_cvt_pk_bf16_f32 v0, v4, s0
	s_nop 0
	v_addc_co_u32_e32 v3, vcc, 0, v3, vcc
	global_store_short v[2:3], v0, off
	v_or_b32_e32 v2, 0x1a0, v50
	v_ashrrev_i32_e32 v3, 31, v2
	v_lshl_add_u64 v[2:3], v[2:3], 1, s[6:7]
	v_add_co_u32_e32 v2, vcc, s26, v2
	v_cvt_pk_bf16_f32 v0, v5, s0
	s_nop 0
	v_addc_co_u32_e32 v3, vcc, 0, v3, vcc
	global_store_short v[2:3], v0, off
	v_or_b32_e32 v2, 0x420, v50
	v_ashrrev_i32_e32 v3, 31, v2
	v_lshl_add_u64 v[2:3], v[2:3], 1, s[6:7]
	v_add_co_u32_e32 v2, vcc, s26, v2
	v_cvt_pk_bf16_f32 v0, v6, s0
	s_nop 0
	v_addc_co_u32_e32 v3, vcc, 0, v3, vcc
	global_store_short v[2:3], v0, off
	v_or_b32_e32 v2, 0x4a0, v50
	v_ashrrev_i32_e32 v3, 31, v2
	v_lshl_add_u64 v[2:3], v[2:3], 1, s[6:7]
	v_add_co_u32_e32 v2, vcc, s26, v2
	v_cvt_pk_bf16_f32 v0, v7, s0
	s_nop 0
	v_addc_co_u32_e32 v3, vcc, 0, v3, vcc
	global_store_short v[2:3], v0, off
	v_or_b32_e32 v2, 0x520, v50
	v_ashrrev_i32_e32 v3, 31, v2
	v_lshl_add_u64 v[2:3], v[2:3], 1, s[6:7]
	v_add_co_u32_e32 v2, vcc, s26, v2
	v_cvt_pk_bf16_f32 v0, v8, s0
	s_nop 0
	v_addc_co_u32_e32 v3, vcc, 0, v3, vcc
	global_store_short v[2:3], v0, off
	v_or_b32_e32 v2, 0x5a0, v50
	v_ashrrev_i32_e32 v3, 31, v2
	v_lshl_add_u64 v[2:3], v[2:3], 1, s[6:7]
	v_add_co_u32_e32 v2, vcc, s26, v2
	v_cvt_pk_bf16_f32 v0, v9, s0
	s_nop 0
	v_addc_co_u32_e32 v3, vcc, 0, v3, vcc
	global_store_short v[2:3], v0, off
	v_add_co_u32_e32 v2, vcc, s26, v84
	v_cvt_pk_bf16_f32 v0, v10, s0
	s_nop 0
	v_addc_co_u32_e32 v3, vcc, 0, v85, vcc
	global_store_short v[2:3], v0, off
	v_add_co_u32_e32 v2, vcc, s26, v86
	v_cvt_pk_bf16_f32 v0, v11, s0
	s_nop 0
	v_addc_co_u32_e32 v3, vcc, 0, v87, vcc
	global_store_short v[2:3], v0, off
	v_add_co_u32_e32 v2, vcc, s26, v88
	v_cvt_pk_bf16_f32 v0, v12, s0
	s_nop 0
	v_addc_co_u32_e32 v3, vcc, 0, v89, vcc
	global_store_short v[2:3], v0, off
	v_add_co_u32_e32 v2, vcc, s26, v90
	v_cvt_pk_bf16_f32 v0, v13, s0
	s_nop 0
	v_addc_co_u32_e32 v3, vcc, 0, v91, vcc
	global_store_short v[2:3], v0, off
	v_add_co_u32_e32 v2, vcc, s26, v92
	v_cvt_pk_bf16_f32 v0, v14, s0
	s_nop 0
	v_addc_co_u32_e32 v3, vcc, 0, v93, vcc
	global_store_short v[2:3], v0, off
	v_add_co_u32_e32 v2, vcc, s26, v94
	v_cvt_pk_bf16_f32 v0, v15, s0
	s_nop 0
	v_addc_co_u32_e32 v3, vcc, 0, v95, vcc
	global_store_short v[2:3], v0, off
	v_add_co_u32_e32 v2, vcc, s26, v96
	v_cvt_pk_bf16_f32 v0, v16, s0
	s_nop 0
	v_addc_co_u32_e32 v3, vcc, 0, v97, vcc
	global_store_short v[2:3], v0, off
	v_add_co_u32_e32 v2, vcc, s26, v98
	v_cvt_pk_bf16_f32 v0, v17, s0
	s_nop 0
	v_addc_co_u32_e32 v3, vcc, 0, v99, vcc
	global_store_short v[2:3], v0, off
	ds_read_b128 v[2:5], v119 offset:34816
	ds_read_b128 v[84:87], v119 offset:34848
	ds_read_b128 v[146:149], v119 offset:34880
	ds_read_b128 v[150:153], v119 offset:34912
	ds_read_b128 v[154:157], v119 offset:34944
	ds_read_b128 v[158:161], v119 offset:34976
	ds_read_b128 v[162:165], v119 offset:35008
	ds_read_b128 v[166:169], v119 offset:35040
	s_waitcnt lgkmcnt(7)
	v_mfma_f32_32x32x16_bf16 v[2:17], v[46:49], v[2:5], 0
	s_waitcnt lgkmcnt(6)
	v_mfma_f32_32x32x16_bf16 v[2:17], v[42:45], v[84:87], v[2:17]
	s_waitcnt lgkmcnt(5)
	v_mfma_f32_32x32x16_bf16 v[2:17], v[38:41], v[146:149], v[2:17]
	s_waitcnt lgkmcnt(4)
	v_mfma_f32_32x32x16_bf16 v[2:17], v[34:37], v[150:153], v[2:17]
	s_waitcnt lgkmcnt(3)
	v_mfma_f32_32x32x16_bf16 v[2:17], v[30:33], v[154:157], v[2:17]
	s_waitcnt lgkmcnt(2)
	v_mfma_f32_32x32x16_bf16 v[2:17], v[26:29], v[158:161], v[2:17]
	s_waitcnt lgkmcnt(1)
	v_mfma_f32_32x32x16_bf16 v[2:17], v[22:25], v[162:165], v[2:17]
	s_waitcnt lgkmcnt(0)
; #define LAS __attribute__((address_space(3)))
; __device__ __forceinline__ unsigned cvt_pk_bf16(float lo, float hi) { const f32v2_t v = {lo, hi}; const bf16v2_t r = __builtin_convertvector(v, bf16v2_t); return __builtin_bit_cast(unsigned, r); }
; __device__ __forceinline__ f32x16 mfma32(bf16x8 a, bf16x8 b, f32x16 c) { return __builtin_amdgcn_mfma_f32_32x32x16_bf16(a, b, c, 0, 0, 0); }
; __device__ __forceinline__ f32x16 zero16() { return (f32x16){0.f, 0.f, 0.f, 0.f, 0.f, 0.f, 0.f, 0.f, 0.f, 0.f, 0.f, 0.f, 0.f, 0.f, 0.f, 0.f}; }
; __device__ __forceinline__ void r1_item(const bf16_t* __restrict__ projT, bf16_t* stloc, const float* __restrict__ cosT, const float* __restrict__ sinT, float lgf2, float lgb2, int item, int seqlen, LAS unsigned char* lds) {
;     ...
;     for (int dir = 0; dir < 2; ++dir) {
;         LAS bf16_t* KT = dir ? KTb : KTf;
;         bf16_t* dst = stloc + ((size_t)(ch * 4 + h) * 2 + dir) * 32768;
; #pragma unroll
;         for (int ct = 0; ct < 4; ++ct) {
;             f32x16 acc = zero16();
; #pragma unroll
;             for (int s = 0; s < 8; ++s) { const bf16x8 bfr = *(const LAS bf16x8*)(KT + (32 * ct + c) * KT_STRIDE + 16 * s + 8 * hh); acc = mfma32(af[s], bfr, acc); }
; #pragma unroll
;             for (int rg = 0; rg < 16; ++rg) { const int dv = 32 * w + (rg & 3) + 8 * (rg >> 2) + 4 * hh; dst[dv * 128 + 32 * ct + c] = (bf16_t)(cvt_pk_bf16(acc[rg], 0.f) & 0xffffu); }
;         }
;     }
	v_mfma_f32_32x32x16_bf16 v[2:17], v[18:21], v[166:169], v[2:17]
	v_or_b32_e32 v84, 64, v50
	v_ashrrev_i32_e32 v85, 31, v84
	v_lshl_add_u64 v[84:85], v[84:85], 1, s[6:7]
	v_add_co_u32_e32 v84, vcc, s26, v84
	s_nop 1
	v_addc_co_u32_e32 v85, vcc, 0, v85, vcc
	s_nop 4
	v_cvt_pk_bf16_f32 v0, v2, s0
	v_or_b32_e32 v2, 0xc0, v50
	global_store_short v[84:85], v0, off
	v_cvt_pk_bf16_f32 v0, v3, s0
	v_ashrrev_i32_e32 v3, 31, v2
	v_lshl_add_u64 v[2:3], v[2:3], 1, s[6:7]
	v_add_co_u32_e32 v2, vcc, s26, v2
	s_nop 1
	v_addc_co_u32_e32 v3, vcc, 0, v3, vcc
	global_store_short v[2:3], v0, off
	v_or_b32_e32 v2, 0x140, v50
	v_ashrrev_i32_e32 v3, 31, v2
	v_lshl_add_u64 v[2:3], v[2:3], 1, s[6:7]
	v_add_co_u32_e32 v2, vcc, s26, v2
	v_cvt_pk_bf16_f32 v0, v4, s0
	s_nop 0
	v_addc_co_u32_e32 v3, vcc, 0, v3, vcc
	global_store_short v[2:3], v0, off
	v_or_b32_e32 v2, 0x1c0, v50
	v_ashrrev_i32_e32 v3, 31, v2
	v_lshl_add_u64 v[2:3], v[2:3], 1, s[6:7]
	v_add_co_u32_e32 v2, vcc, s26, v2
	v_cvt_pk_bf16_f32 v0, v5, s0
	s_nop 0
	v_addc_co_u32_e32 v3, vcc, 0, v3, vcc
	global_store_short v[2:3], v0, off
	v_or_b32_e32 v2, 0x440, v50
	v_ashrrev_i32_e32 v3, 31, v2
	v_lshl_add_u64 v[2:3], v[2:3], 1, s[6:7]
	v_add_co_u32_e32 v2, vcc, s26, v2
	v_cvt_pk_bf16_f32 v0, v6, s0
	s_nop 0
	v_addc_co_u32_e32 v3, vcc, 0, v3, vcc
	global_store_short v[2:3], v0, off
	v_or_b32_e32 v2, 0x4c0, v50
	v_ashrrev_i32_e32 v3, 31, v2
	v_lshl_add_u64 v[2:3], v[2:3], 1, s[6:7]
	v_add_co_u32_e32 v2, vcc, s26, v2
	v_cvt_pk_bf16_f32 v0, v7, s0
	s_nop 0
	v_addc_co_u32_e32 v3, vcc, 0, v3, vcc
	global_store_short v[2:3], v0, off
	v_or_b32_e32 v2, 0x540, v50
	v_ashrrev_i32_e32 v3, 31, v2
	v_lshl_add_u64 v[2:3], v[2:3], 1, s[6:7]
	v_add_co_u32_e32 v2, vcc, s26, v2
	v_cvt_pk_bf16_f32 v0, v8, s0
	s_nop 0
	v_addc_co_u32_e32 v3, vcc, 0, v3, vcc
	global_store_short v[2:3], v0, off
	v_or_b32_e32 v2, 0x5c0, v50
	v_ashrrev_i32_e32 v3, 31, v2
	v_lshl_add_u64 v[2:3], v[2:3], 1, s[6:7]
	v_add_co_u32_e32 v2, vcc, s26, v2
	v_cvt_pk_bf16_f32 v0, v9, s0
	s_nop 0
	v_addc_co_u32_e32 v3, vcc, 0, v3, vcc
	global_store_short v[2:3], v0, off
	v_add_co_u32_e32 v2, vcc, s26, v68
	v_cvt_pk_bf16_f32 v0, v10, s0
	s_nop 0
	v_addc_co_u32_e32 v3, vcc, 0, v69, vcc
	global_store_short v[2:3], v0, off
	v_add_co_u32_e32 v2, vcc, s26, v70
	v_cvt_pk_bf16_f32 v0, v11, s0
	s_nop 0
	v_addc_co_u32_e32 v3, vcc, 0, v71, vcc
	global_store_short v[2:3], v0, off
	v_add_co_u32_e32 v2, vcc, s26, v72
	v_cvt_pk_bf16_f32 v0, v12, s0
	s_nop 0
	v_addc_co_u32_e32 v3, vcc, 0, v73, vcc
	global_store_short v[2:3], v0, off
	v_add_co_u32_e32 v2, vcc, s26, v74
	v_cvt_pk_bf16_f32 v0, v13, s0
	s_nop 0
	v_addc_co_u32_e32 v3, vcc, 0, v75, vcc
	global_store_short v[2:3], v0, off
	v_add_co_u32_e32 v2, vcc, s26, v76
	v_cvt_pk_bf16_f32 v0, v14, s0
	s_nop 0
	v_addc_co_u32_e32 v3, vcc, 0, v77, vcc
	global_store_short v[2:3], v0, off
	v_add_co_u32_e32 v2, vcc, s26, v78
	v_cvt_pk_bf16_f32 v0, v15, s0
	s_nop 0
	v_addc_co_u32_e32 v3, vcc, 0, v79, vcc
	global_store_short v[2:3], v0, off
	v_add_co_u32_e32 v2, vcc, s26, v80
	v_cvt_pk_bf16_f32 v0, v16, s0
	s_nop 0
	v_addc_co_u32_e32 v3, vcc, 0, v81, vcc
	global_store_short v[2:3], v0, off
	v_add_co_u32_e32 v2, vcc, s26, v82
	v_cvt_pk_bf16_f32 v0, v17, s0
	s_nop 0
	v_addc_co_u32_e32 v3, vcc, 0, v83, vcc
	global_store_short v[2:3], v0, off
	ds_read_b128 v[2:5], v51 offset:34816
	ds_read_b128 v[68:71], v51 offset:34848
	ds_read_b128 v[146:149], v51 offset:34880
	ds_read_b128 v[150:153], v51 offset:34912
	ds_read_b128 v[154:157], v51 offset:34944
	ds_read_b128 v[158:161], v51 offset:34976
	ds_read_b128 v[162:165], v51 offset:35008
	ds_read_b128 v[166:169], v51 offset:35040
	s_waitcnt lgkmcnt(7)
	v_mfma_f32_32x32x16_bf16 v[2:17], v[46:49], v[2:5], 0
	s_waitcnt lgkmcnt(6)
	v_mfma_f32_32x32x16_bf16 v[2:17], v[42:45], v[68:71], v[2:17]
	s_waitcnt lgkmcnt(5)
; #define LAS __attribute__((address_space(3)))
; __device__ __forceinline__ unsigned cvt_pk_bf16(float lo, float hi) { const f32v2_t v = {lo, hi}; const bf16v2_t r = __builtin_convertvector(v, bf16v2_t); return __builtin_bit_cast(unsigned, r); }
; __device__ __forceinline__ f32x16 mfma32(bf16x8 a, bf16x8 b, f32x16 c) { return __builtin_amdgcn_mfma_f32_32x32x16_bf16(a, b, c, 0, 0, 0); }
; __device__ __forceinline__ f32x16 zero16() { return (f32x16){0.f, 0.f, 0.f, 0.f, 0.f, 0.f, 0.f, 0.f, 0.f, 0.f, 0.f, 0.f, 0.f, 0.f, 0.f, 0.f}; }
; __device__ __forceinline__ void r1_item(const bf16_t* __restrict__ projT, bf16_t* stloc, const float* __restrict__ cosT, const float* __restrict__ sinT, float lgf2, float lgb2, int item, int seqlen, LAS unsigned char* lds) {
;     ...
;     for (int dir = 0; dir < 2; ++dir) {
;         LAS bf16_t* KT = dir ? KTb : KTf;
;         bf16_t* dst = stloc + ((size_t)(ch * 4 + h) * 2 + dir) * 32768;
; #pragma unroll
;         for (int ct = 0; ct < 4; ++ct) {
;             f32x16 acc = zero16();
; #pragma unroll
;             for (int s = 0; s < 8; ++s) { const bf16x8 bfr = *(const LAS bf16x8*)(KT + (32 * ct + c) * KT_STRIDE + 16 * s + 8 * hh); acc = mfma32(af[s], bfr, acc); }
; #pragma unroll
;             for (int rg = 0; rg < 16; ++rg) { const int dv = 32 * w + (rg & 3) + 8 * (rg >> 2) + 4 * hh; dst[dv * 128 + 32 * ct + c] = (bf16_t)(cvt_pk_bf16(acc[rg], 0.f) & 0xffffu); }
;         }
;     }
;     __syncthreads();
	v_mfma_f32_32x32x16_bf16 v[2:17], v[38:41], v[146:149], v[2:17]
	s_waitcnt lgkmcnt(4)
	v_mfma_f32_32x32x16_bf16 v[2:17], v[34:37], v[150:153], v[2:17]
	s_waitcnt lgkmcnt(3)
	v_mfma_f32_32x32x16_bf16 v[2:17], v[30:33], v[154:157], v[2:17]
	s_waitcnt lgkmcnt(2)
	v_mfma_f32_32x32x16_bf16 v[2:17], v[26:29], v[158:161], v[2:17]
	s_waitcnt lgkmcnt(1)
	v_mfma_f32_32x32x16_bf16 v[2:17], v[22:25], v[162:165], v[2:17]
	s_waitcnt lgkmcnt(0)
	v_mfma_f32_32x32x16_bf16 v[2:17], v[18:21], v[166:169], v[2:17]
	v_or_b32_e32 v18, 0x60, v50
	v_ashrrev_i32_e32 v19, 31, v18
	v_lshl_add_u64 v[18:19], v[18:19], 1, s[6:7]
	v_add_co_u32_e32 v18, vcc, s26, v18
	s_nop 1
	v_addc_co_u32_e32 v19, vcc, 0, v19, vcc
	s_nop 4
	v_cvt_pk_bf16_f32 v0, v2, s0
	v_or_b32_e32 v2, 0xe0, v50
	global_store_short v[18:19], v0, off
	v_cvt_pk_bf16_f32 v0, v3, s0
	v_ashrrev_i32_e32 v3, 31, v2
	v_lshl_add_u64 v[2:3], v[2:3], 1, s[6:7]
	v_add_co_u32_e32 v2, vcc, s26, v2
	s_nop 1
	v_addc_co_u32_e32 v3, vcc, 0, v3, vcc
	global_store_short v[2:3], v0, off
	v_or_b32_e32 v2, 0x160, v50
	v_ashrrev_i32_e32 v3, 31, v2
	v_lshl_add_u64 v[2:3], v[2:3], 1, s[6:7]
	v_add_co_u32_e32 v2, vcc, s26, v2
	v_cvt_pk_bf16_f32 v0, v4, s0
	s_nop 0
	v_addc_co_u32_e32 v3, vcc, 0, v3, vcc
	global_store_short v[2:3], v0, off
	v_or_b32_e32 v2, 0x1e0, v50
	v_ashrrev_i32_e32 v3, 31, v2
	v_lshl_add_u64 v[2:3], v[2:3], 1, s[6:7]
	v_add_co_u32_e32 v2, vcc, s26, v2
	v_cvt_pk_bf16_f32 v0, v5, s0
	s_nop 0
	v_addc_co_u32_e32 v3, vcc, 0, v3, vcc
	global_store_short v[2:3], v0, off
	v_or_b32_e32 v2, 0x460, v50
	v_ashrrev_i32_e32 v3, 31, v2
	v_lshl_add_u64 v[2:3], v[2:3], 1, s[6:7]
	v_add_co_u32_e32 v2, vcc, s26, v2
	v_cvt_pk_bf16_f32 v0, v6, s0
	s_nop 0
	v_addc_co_u32_e32 v3, vcc, 0, v3, vcc
	global_store_short v[2:3], v0, off
	v_or_b32_e32 v2, 0x4e0, v50
	v_ashrrev_i32_e32 v3, 31, v2
	v_lshl_add_u64 v[2:3], v[2:3], 1, s[6:7]
	v_add_co_u32_e32 v2, vcc, s26, v2
	v_cvt_pk_bf16_f32 v0, v7, s0
	s_nop 0
	v_addc_co_u32_e32 v3, vcc, 0, v3, vcc
	global_store_short v[2:3], v0, off
	v_or_b32_e32 v2, 0x560, v50
	v_ashrrev_i32_e32 v3, 31, v2
	v_lshl_add_u64 v[2:3], v[2:3], 1, s[6:7]
	v_add_co_u32_e32 v2, vcc, s26, v2
	v_cvt_pk_bf16_f32 v0, v8, s0
	s_nop 0
	v_addc_co_u32_e32 v3, vcc, 0, v3, vcc
	global_store_short v[2:3], v0, off
	v_or_b32_e32 v2, 0x5e0, v50
	v_ashrrev_i32_e32 v3, 31, v2
	v_lshl_add_u64 v[2:3], v[2:3], 1, s[6:7]
	v_add_co_u32_e32 v2, vcc, s26, v2
	v_cvt_pk_bf16_f32 v0, v9, s0
	s_nop 0
	v_addc_co_u32_e32 v3, vcc, 0, v3, vcc
	global_store_short v[2:3], v0, off
	v_add_co_u32_e32 v2, vcc, s26, v66
	v_cvt_pk_bf16_f32 v0, v10, s0
	s_nop 0
	v_addc_co_u32_e32 v3, vcc, 0, v67, vcc
	global_store_short v[2:3], v0, off
	v_add_co_u32_e32 v2, vcc, s26, v64
	v_cvt_pk_bf16_f32 v0, v11, s0
	s_nop 0
	v_addc_co_u32_e32 v3, vcc, 0, v65, vcc
	global_store_short v[2:3], v0, off
	v_add_co_u32_e32 v2, vcc, s26, v62
	v_cvt_pk_bf16_f32 v0, v12, s0
	s_nop 0
	v_addc_co_u32_e32 v3, vcc, 0, v63, vcc
	global_store_short v[2:3], v0, off
	v_add_co_u32_e32 v2, vcc, s26, v60
	v_cvt_pk_bf16_f32 v0, v13, s0
	s_nop 0
	v_addc_co_u32_e32 v3, vcc, 0, v61, vcc
	global_store_short v[2:3], v0, off
	v_add_co_u32_e32 v2, vcc, s26, v58
	v_cvt_pk_bf16_f32 v0, v14, s0
	s_nop 0
	v_addc_co_u32_e32 v3, vcc, 0, v59, vcc
	global_store_short v[2:3], v0, off
	v_add_co_u32_e32 v2, vcc, s26, v56
	v_cvt_pk_bf16_f32 v0, v15, s0
	s_nop 0
	v_addc_co_u32_e32 v3, vcc, 0, v57, vcc
	global_store_short v[2:3], v0, off
	v_add_co_u32_e32 v2, vcc, s26, v54
	v_cvt_pk_bf16_f32 v0, v16, s0
	s_nop 0
	v_addc_co_u32_e32 v3, vcc, 0, v55, vcc
	global_store_short v[2:3], v0, off
	v_cvt_pk_bf16_f32 v0, v17, s0
	s_add_u32 s0, s0, s54
	v_add_co_u32_e32 v2, vcc, s26, v52
	s_addc_u32 s1, s1, s55
	s_nop 0
	v_addc_co_u32_e32 v3, vcc, 0, v53, vcc
	s_cmpk_gt_i32 s42, 0x1ff
	global_store_short v[2:3], v0, off
	s_waitcnt vmcnt(63) expcnt(7) lgkmcnt(15)
	s_barrier
	s_cbranch_scc0 .LBB0_361
